# v10 + level0 inverse (spectrum product) loops: khat global loads run 3 iterations ahead
# speedup vs baseline: 1.0154x; 1.0041x over previous
; DI float2 twid(float r) { return float2{__builtin_amdgcn_cosf(r), -__builtin_amdgcn_sinf(r)}; }
; DI void bfly_inv(float2 s0, float2 s1, float2 s2, float2 s3, float r, float2& o0, float2& o1, float2& o2, float2& o3) {
;   float2 w1 = twid(r), w2 = cmul(w1, w1), w3 = cmul(w2, w1);
;   float2 c0 = s0, c1 = cmulc(s1, w1), c2 = cmulc(s2, w2), c3 = cmulc(s3, w3);
;   float2 t0 = {c0.x + c2.x, c0.y + c2.y}, t1 = {c0.x - c2.x, c0.y - c2.y}, t2 = {c1.x + c3.x, c1.y + c3.y}, t3 = {c1.x - c3.x, c1.y - c3.y};
;   o0 = float2{t0.x + t2.x, t0.y + t2.y}; o2 = float2{t0.x - t2.x, t0.y - t2.y}; o1 = float2{t1.x - t3.y, t1.y + t3.x}; o3 = float2{t1.x + t3.y, t1.y - t3.x};
; }
;   for (int bb = tid; bb < NBT * (N / 4); bb += NTHR) { const int b = bb & (N / 4 - 1); float2* z = z0 + (bb / (N / 4)) * N; const int base = b * 4; f32x4 k01 = *(const f32x4*)(kh + base), k23 = *(const f32x4*)(kh + base + 2); float2 o0, o1, o2, o3;
;     bfly_inv(cmul(z[base], float2{k01[0], k01[1]}), cmul(z[base + 1], float2{k01[2], k01[3]}), cmul(z[base + 2], float2{k23[0], k23[1]}), cmul(z[base + 3], float2{k23[2], k23[3]}), 0.f, o0, o1, o2, o3);
;     z[base] = o0; z[base + 1] = o1; z[base + 2] = o2; z[base + 3] = o3; }
;   __syncthreads();
.LBB0_1612:
	v_mov_b32_e32 v218, v2
	v_lshlrev_b32_e32 v219, 3, v218
	v_and_b32_e32 v220, 0xffe0, v219
	global_load_dwordx4 v[222:225], v220, s[80:81] offset:16
	global_load_dwordx4 v[226:229], v220, s[80:81]
	v_add_u32_e32 v218, 0x800, v218
	v_lshlrev_b32_e32 v219, 3, v218
	v_and_b32_e32 v220, 0xffe0, v219
	global_load_dwordx4 v[230:233], v220, s[80:81] offset:16
	global_load_dwordx4 v[234:237], v220, s[80:81]
	v_add_u32_e32 v218, 0x800, v218
	v_lshlrev_b32_e32 v219, 3, v218
	v_and_b32_e32 v220, 0xffe0, v219
	global_load_dwordx4 v[242:245], v220, s[80:81] offset:16
	global_load_dwordx4 v[246:249], v220, s[80:81]
	v_add_u32_e32 v218, 0x800, v218
	v_ashrrev_i32_e32 v4, 31, v3
	v_lshrrev_b32_e32 v4, 21, v4
	v_add_lshl_u32 v4, v3, v4, 5
	v_and_b32_e32 v12, 0xffff0000, v4
	v_lshlrev_b32_e32 v4, 3, v2
	v_and_b32_e32 v13, 0xffe0, v4
	s_nop 0
	v_add3_u32 v17, 16, v12, v13
	ds_read_b128 v[18:21], v17
	ds_read_b128 v[22:25], v17 offset:16
	s_nop 0
	v_add_u32_e32 v2, 0x800, v2
	s_nop 0
	s_waitcnt vmcnt(4) lgkmcnt(1)
	v_pk_mul_f32 v[12:13], v[226:227], v[18:19] op_sel:[1,1] op_sel_hi:[0,1]
	s_nop 0
	v_pk_fma_f32 v[26:27], v[226:227], v[18:19], v[12:13] neg_lo:[0,0,1] neg_hi:[0,0,1]
	v_pk_fma_f32 v[226:227], v[226:227], v[18:19], v[12:13] op_sel_hi:[1,0,1]
	s_nop 0
	v_mov_b32_e32 v226, v21
	v_mov_b32_e32 v27, v227
	v_pk_mul_f32 v[226:227], v[228:229], v[226:227] op_sel:[1,0] op_sel_hi:[0,0]
	s_nop 0
	v_pk_fma_f32 v[12:13], v[228:229], v[20:21], v[226:227] op_sel_hi:[1,0,1] neg_lo:[0,0,1] neg_hi:[0,0,1]
	v_pk_fma_f32 v[226:227], v[228:229], v[20:21], v[226:227] op_sel_hi:[1,0,1]
	s_waitcnt lgkmcnt(0)
	v_pk_mul_f32 v[228:229], v[222:223], v[22:23] op_sel:[1,1] op_sel_hi:[0,1]
	s_nop 0
	v_pk_fma_f32 v[18:19], v[222:223], v[22:23], v[228:229] op_sel_hi:[1,0,1] neg_lo:[0,0,1] neg_hi:[0,0,1]
	v_pk_fma_f32 v[222:223], v[222:223], v[22:23], v[228:229] op_sel_hi:[1,0,1]
	v_mov_b32_e32 v228, v25
	v_pk_mul_f32 v[228:229], v[224:225], v[228:229] op_sel:[1,0] op_sel_hi:[0,0]
	s_nop 0
	v_pk_fma_f32 v[20:21], v[224:225], v[24:25], v[228:229] op_sel_hi:[1,0,1] neg_lo:[0,0,1] neg_hi:[0,0,1]
	v_pk_fma_f32 v[224:225], v[224:225], v[24:25], v[228:229] op_sel_hi:[1,0,1]
	v_pk_mov_b32 v[228:229], v[226:227], v[12:13] op_sel:[1,0]
	s_nop 0
	v_pk_fma_f32 v[12:13], v[228:229], 0, v[12:13] op_sel_hi:[1,0,1] neg_lo:[1,0,0] neg_hi:[1,0,0]
	v_pk_fma_f32 v[226:227], v[228:229], 0, v[226:227] op_sel_hi:[1,0,1]
	s_nop 0
	v_mov_b32_e32 v13, v227
	v_pk_mov_b32 v[226:227], v[222:223], v[18:19] op_sel:[1,0]
	s_nop 0
	v_pk_fma_f32 v[228:229], v[226:227], 0, v[18:19] op_sel_hi:[1,0,1] neg_lo:[1,0,0] neg_hi:[1,0,0]
	v_pk_fma_f32 v[222:223], v[226:227], 0, v[222:223] op_sel_hi:[1,0,1]
	s_nop 0
	v_mov_b32_e32 v229, v223
	v_pk_mov_b32 v[222:223], v[224:225], v[20:21] op_sel:[1,0]
	v_pk_add_f32 v[18:19], v[26:27], v[228:229]
	v_pk_fma_f32 v[226:227], v[222:223], 0, v[20:21] op_sel_hi:[1,0,1] neg_lo:[1,0,0] neg_hi:[1,0,0]
	v_pk_fma_f32 v[222:223], v[222:223], 0, v[224:225] op_sel_hi:[1,0,1]
	v_pk_add_f32 v[224:225], v[26:27], v[228:229] neg_lo:[0,1] neg_hi:[0,1]
	v_mov_b32_e32 v227, v223
	v_pk_add_f32 v[20:21], v[12:13], v[226:227]
	v_pk_add_f32 v[226:227], v[12:13], v[226:227] neg_lo:[0,1] neg_hi:[0,1]
	v_pk_add_f32 v[222:223], v[18:19], v[20:21]
	v_pk_add_f32 v[228:229], v[224:225], v[226:227] op_sel:[0,1] op_sel_hi:[1,0] neg_lo:[0,1] neg_hi:[0,1]
	v_pk_add_f32 v[226:227], v[224:225], v[226:227] op_sel:[0,1] op_sel_hi:[1,0]
	v_mov_b32_e32 v224, v228
	v_mov_b32_e32 v225, v227
	ds_write_b128 v17, v[222:225]
	v_add_u32_e32 v222, 0x200, v3
	v_pk_add_f32 v[224:225], v[18:19], v[20:21] neg_lo:[0,1] neg_hi:[0,1]
	v_mov_b32_e32 v227, v229
	v_mov_b32_e32 v3, v222
	ds_write_b128 v17, v[224:227] offset:16
	s_nop 0
	v_lshlrev_b32_e32 v219, 3, v218
	v_and_b32_e32 v220, 0xffe0, v219
	global_load_dwordx4 v[222:225], v220, s[80:81] offset:16
	global_load_dwordx4 v[226:229], v220, s[80:81]
	v_add_u32_e32 v218, 0x800, v218
	v_ashrrev_i32_e32 v4, 31, v3
	v_lshrrev_b32_e32 v4, 21, v4
	v_add_lshl_u32 v4, v3, v4, 5
	v_and_b32_e32 v12, 0xffff0000, v4
	v_lshlrev_b32_e32 v4, 3, v2
	v_and_b32_e32 v13, 0xffe0, v4
	s_nop 0
	v_add3_u32 v17, 16, v12, v13
	ds_read_b128 v[18:21], v17
	ds_read_b128 v[22:25], v17 offset:16
	s_nop 0
	v_add_u32_e32 v2, 0x800, v2
	s_nop 0
	s_waitcnt vmcnt(4) lgkmcnt(1)
	v_pk_mul_f32 v[12:13], v[234:235], v[18:19] op_sel:[1,1] op_sel_hi:[0,1]
	s_nop 0
	v_pk_fma_f32 v[26:27], v[234:235], v[18:19], v[12:13] neg_lo:[0,0,1] neg_hi:[0,0,1]
	v_pk_fma_f32 v[234:235], v[234:235], v[18:19], v[12:13] op_sel_hi:[1,0,1]
	s_nop 0
	v_mov_b32_e32 v234, v21
	v_mov_b32_e32 v27, v235
	v_pk_mul_f32 v[234:235], v[236:237], v[234:235] op_sel:[1,0] op_sel_hi:[0,0]
	s_nop 0
	v_pk_fma_f32 v[12:13], v[236:237], v[20:21], v[234:235] op_sel_hi:[1,0,1] neg_lo:[0,0,1] neg_hi:[0,0,1]
	v_pk_fma_f32 v[234:235], v[236:237], v[20:21], v[234:235] op_sel_hi:[1,0,1]
	s_waitcnt lgkmcnt(0)
; DI float2 twid(float r) { return float2{__builtin_amdgcn_cosf(r), -__builtin_amdgcn_sinf(r)}; }
; DI void bfly_inv(float2 s0, float2 s1, float2 s2, float2 s3, float r, float2& o0, float2& o1, float2& o2, float2& o3) {
;   float2 w1 = twid(r), w2 = cmul(w1, w1), w3 = cmul(w2, w1);
;   float2 c0 = s0, c1 = cmulc(s1, w1), c2 = cmulc(s2, w2), c3 = cmulc(s3, w3);
;   float2 t0 = {c0.x + c2.x, c0.y + c2.y}, t1 = {c0.x - c2.x, c0.y - c2.y}, t2 = {c1.x + c3.x, c1.y + c3.y}, t3 = {c1.x - c3.x, c1.y - c3.y};
;   o0 = float2{t0.x + t2.x, t0.y + t2.y}; o2 = float2{t0.x - t2.x, t0.y - t2.y}; o1 = float2{t1.x - t3.y, t1.y + t3.x}; o3 = float2{t1.x + t3.y, t1.y - t3.x};
; }
;   for (int bb = tid; bb < NBT * (N / 4); bb += NTHR) { const int b = bb & (N / 4 - 1); float2* z = z0 + (bb / (N / 4)) * N; const int base = b * 4; f32x4 k01 = *(const f32x4*)(kh + base), k23 = *(const f32x4*)(kh + base + 2); float2 o0, o1, o2, o3;
;     bfly_inv(cmul(z[base], float2{k01[0], k01[1]}), cmul(z[base + 1], float2{k01[2], k01[3]}), cmul(z[base + 2], float2{k23[0], k23[1]}), cmul(z[base + 3], float2{k23[2], k23[3]}), 0.f, o0, o1, o2, o3);
;     z[base] = o0; z[base + 1] = o1; z[base + 2] = o2; z[base + 3] = o3; }
;   __syncthreads();
	v_pk_mul_f32 v[236:237], v[230:231], v[22:23] op_sel:[1,1] op_sel_hi:[0,1]
	s_nop 0
	v_pk_fma_f32 v[18:19], v[230:231], v[22:23], v[236:237] op_sel_hi:[1,0,1] neg_lo:[0,0,1] neg_hi:[0,0,1]
	v_pk_fma_f32 v[230:231], v[230:231], v[22:23], v[236:237] op_sel_hi:[1,0,1]
	v_mov_b32_e32 v236, v25
	v_pk_mul_f32 v[236:237], v[232:233], v[236:237] op_sel:[1,0] op_sel_hi:[0,0]
	s_nop 0
	v_pk_fma_f32 v[20:21], v[232:233], v[24:25], v[236:237] op_sel_hi:[1,0,1] neg_lo:[0,0,1] neg_hi:[0,0,1]
	v_pk_fma_f32 v[232:233], v[232:233], v[24:25], v[236:237] op_sel_hi:[1,0,1]
	v_pk_mov_b32 v[236:237], v[234:235], v[12:13] op_sel:[1,0]
	s_nop 0
	v_pk_fma_f32 v[12:13], v[236:237], 0, v[12:13] op_sel_hi:[1,0,1] neg_lo:[1,0,0] neg_hi:[1,0,0]
	v_pk_fma_f32 v[234:235], v[236:237], 0, v[234:235] op_sel_hi:[1,0,1]
	s_nop 0
	v_mov_b32_e32 v13, v235
	v_pk_mov_b32 v[234:235], v[230:231], v[18:19] op_sel:[1,0]
	s_nop 0
	v_pk_fma_f32 v[236:237], v[234:235], 0, v[18:19] op_sel_hi:[1,0,1] neg_lo:[1,0,0] neg_hi:[1,0,0]
	v_pk_fma_f32 v[230:231], v[234:235], 0, v[230:231] op_sel_hi:[1,0,1]
	s_nop 0
	v_mov_b32_e32 v237, v231
	v_pk_mov_b32 v[230:231], v[232:233], v[20:21] op_sel:[1,0]
	v_pk_add_f32 v[18:19], v[26:27], v[236:237]
	v_pk_fma_f32 v[234:235], v[230:231], 0, v[20:21] op_sel_hi:[1,0,1] neg_lo:[1,0,0] neg_hi:[1,0,0]
	v_pk_fma_f32 v[230:231], v[230:231], 0, v[232:233] op_sel_hi:[1,0,1]
	v_pk_add_f32 v[232:233], v[26:27], v[236:237] neg_lo:[0,1] neg_hi:[0,1]
	v_mov_b32_e32 v235, v231
	v_pk_add_f32 v[20:21], v[12:13], v[234:235]
	v_pk_add_f32 v[234:235], v[12:13], v[234:235] neg_lo:[0,1] neg_hi:[0,1]
	v_pk_add_f32 v[230:231], v[18:19], v[20:21]
	v_pk_add_f32 v[236:237], v[232:233], v[234:235] op_sel:[0,1] op_sel_hi:[1,0] neg_lo:[0,1] neg_hi:[0,1]
	v_pk_add_f32 v[234:235], v[232:233], v[234:235] op_sel:[0,1] op_sel_hi:[1,0]
	v_mov_b32_e32 v232, v236
	v_mov_b32_e32 v233, v235
	ds_write_b128 v17, v[230:233]
	v_add_u32_e32 v230, 0x200, v3
	v_pk_add_f32 v[232:233], v[18:19], v[20:21] neg_lo:[0,1] neg_hi:[0,1]
	v_mov_b32_e32 v235, v237
	v_mov_b32_e32 v3, v230
	ds_write_b128 v17, v[232:235] offset:16
	s_nop 0
	v_lshlrev_b32_e32 v219, 3, v218
	v_and_b32_e32 v220, 0xffe0, v219
	global_load_dwordx4 v[230:233], v220, s[80:81] offset:16
	global_load_dwordx4 v[234:237], v220, s[80:81]
	v_add_u32_e32 v218, 0x800, v218
	v_ashrrev_i32_e32 v4, 31, v3
	v_lshrrev_b32_e32 v4, 21, v4
	v_add_lshl_u32 v4, v3, v4, 5
	v_and_b32_e32 v12, 0xffff0000, v4
	v_lshlrev_b32_e32 v4, 3, v2
	v_and_b32_e32 v13, 0xffe0, v4
	s_nop 0
	v_add3_u32 v17, 16, v12, v13
	ds_read_b128 v[18:21], v17
	ds_read_b128 v[22:25], v17 offset:16
	s_nop 0
	v_add_u32_e32 v2, 0x800, v2
	s_nop 0
	s_waitcnt vmcnt(4) lgkmcnt(1)
	v_pk_mul_f32 v[12:13], v[246:247], v[18:19] op_sel:[1,1] op_sel_hi:[0,1]
	s_nop 0
	v_pk_fma_f32 v[26:27], v[246:247], v[18:19], v[12:13] neg_lo:[0,0,1] neg_hi:[0,0,1]
	v_pk_fma_f32 v[246:247], v[246:247], v[18:19], v[12:13] op_sel_hi:[1,0,1]
	s_nop 0
	v_mov_b32_e32 v246, v21
	v_mov_b32_e32 v27, v247
	v_pk_mul_f32 v[246:247], v[248:249], v[246:247] op_sel:[1,0] op_sel_hi:[0,0]
	s_nop 0
	v_pk_fma_f32 v[12:13], v[248:249], v[20:21], v[246:247] op_sel_hi:[1,0,1] neg_lo:[0,0,1] neg_hi:[0,0,1]
	v_pk_fma_f32 v[246:247], v[248:249], v[20:21], v[246:247] op_sel_hi:[1,0,1]
	s_waitcnt lgkmcnt(0)
	v_pk_mul_f32 v[248:249], v[242:243], v[22:23] op_sel:[1,1] op_sel_hi:[0,1]
	s_nop 0
	v_pk_fma_f32 v[18:19], v[242:243], v[22:23], v[248:249] op_sel_hi:[1,0,1] neg_lo:[0,0,1] neg_hi:[0,0,1]
	v_pk_fma_f32 v[242:243], v[242:243], v[22:23], v[248:249] op_sel_hi:[1,0,1]
	v_mov_b32_e32 v248, v25
	v_pk_mul_f32 v[248:249], v[244:245], v[248:249] op_sel:[1,0] op_sel_hi:[0,0]
	s_nop 0
	v_pk_fma_f32 v[20:21], v[244:245], v[24:25], v[248:249] op_sel_hi:[1,0,1] neg_lo:[0,0,1] neg_hi:[0,0,1]
	v_pk_fma_f32 v[244:245], v[244:245], v[24:25], v[248:249] op_sel_hi:[1,0,1]
	v_pk_mov_b32 v[248:249], v[246:247], v[12:13] op_sel:[1,0]
	s_nop 0
	v_pk_fma_f32 v[12:13], v[248:249], 0, v[12:13] op_sel_hi:[1,0,1] neg_lo:[1,0,0] neg_hi:[1,0,0]
	v_pk_fma_f32 v[246:247], v[248:249], 0, v[246:247] op_sel_hi:[1,0,1]
	s_nop 0
	v_mov_b32_e32 v13, v247
	v_pk_mov_b32 v[246:247], v[242:243], v[18:19] op_sel:[1,0]
	s_nop 0
	v_pk_fma_f32 v[248:249], v[246:247], 0, v[18:19] op_sel_hi:[1,0,1] neg_lo:[1,0,0] neg_hi:[1,0,0]
	v_pk_fma_f32 v[242:243], v[246:247], 0, v[242:243] op_sel_hi:[1,0,1]
	s_nop 0
	v_mov_b32_e32 v249, v243
	v_pk_mov_b32 v[242:243], v[244:245], v[20:21] op_sel:[1,0]
	v_pk_add_f32 v[18:19], v[26:27], v[248:249]
	v_pk_fma_f32 v[246:247], v[242:243], 0, v[20:21] op_sel_hi:[1,0,1] neg_lo:[1,0,0] neg_hi:[1,0,0]
	v_pk_fma_f32 v[242:243], v[242:243], 0, v[244:245] op_sel_hi:[1,0,1]
	v_pk_add_f32 v[244:245], v[26:27], v[248:249] neg_lo:[0,1] neg_hi:[0,1]
	v_mov_b32_e32 v247, v243
	v_pk_add_f32 v[20:21], v[12:13], v[246:247]
	v_pk_add_f32 v[246:247], v[12:13], v[246:247] neg_lo:[0,1] neg_hi:[0,1]
	v_pk_add_f32 v[242:243], v[18:19], v[20:21]
	v_pk_add_f32 v[248:249], v[244:245], v[246:247] op_sel:[0,1] op_sel_hi:[1,0] neg_lo:[0,1] neg_hi:[0,1]
	v_pk_add_f32 v[246:247], v[244:245], v[246:247] op_sel:[0,1] op_sel_hi:[1,0]
	v_mov_b32_e32 v244, v248
	v_mov_b32_e32 v245, v247
	ds_write_b128 v17, v[242:245]
	v_add_u32_e32 v242, 0x200, v3
	v_pk_add_f32 v[244:245], v[18:19], v[20:21] neg_lo:[0,1] neg_hi:[0,1]
	v_mov_b32_e32 v247, v249
	v_mov_b32_e32 v3, v242
	ds_write_b128 v17, v[244:247] offset:16
	s_nop 0
	v_lshlrev_b32_e32 v219, 3, v218
	v_and_b32_e32 v220, 0xffe0, v219
	global_load_dwordx4 v[242:245], v220, s[80:81] offset:16
	global_load_dwordx4 v[246:249], v220, s[80:81]
	v_add_u32_e32 v218, 0x800, v218
	v_ashrrev_i32_e32 v4, 31, v3
	v_lshrrev_b32_e32 v4, 21, v4
	v_add_lshl_u32 v4, v3, v4, 5
	v_and_b32_e32 v12, 0xffff0000, v4
	v_lshlrev_b32_e32 v4, 3, v2
	v_and_b32_e32 v13, 0xffe0, v4
	s_nop 0
	v_add3_u32 v17, 16, v12, v13
	ds_read_b128 v[18:21], v17
	ds_read_b128 v[22:25], v17 offset:16
	s_nop 0
	v_add_u32_e32 v2, 0x800, v2
	s_nop 0
	s_waitcnt vmcnt(4) lgkmcnt(1)
; DI float2 twid(float r) { return float2{__builtin_amdgcn_cosf(r), -__builtin_amdgcn_sinf(r)}; }
; DI void bfly_inv(float2 s0, float2 s1, float2 s2, float2 s3, float r, float2& o0, float2& o1, float2& o2, float2& o3) {
;   float2 w1 = twid(r), w2 = cmul(w1, w1), w3 = cmul(w2, w1);
;   float2 c0 = s0, c1 = cmulc(s1, w1), c2 = cmulc(s2, w2), c3 = cmulc(s3, w3);
;   float2 t0 = {c0.x + c2.x, c0.y + c2.y}, t1 = {c0.x - c2.x, c0.y - c2.y}, t2 = {c1.x + c3.x, c1.y + c3.y}, t3 = {c1.x - c3.x, c1.y - c3.y};
;   o0 = float2{t0.x + t2.x, t0.y + t2.y}; o2 = float2{t0.x - t2.x, t0.y - t2.y}; o1 = float2{t1.x - t3.y, t1.y + t3.x}; o3 = float2{t1.x + t3.y, t1.y - t3.x};
; }
;   for (int bb = tid; bb < NBT * (N / 4); bb += NTHR) { const int b = bb & (N / 4 - 1); float2* z = z0 + (bb / (N / 4)) * N; const int base = b * 4; f32x4 k01 = *(const f32x4*)(kh + base), k23 = *(const f32x4*)(kh + base + 2); float2 o0, o1, o2, o3;
;     bfly_inv(cmul(z[base], float2{k01[0], k01[1]}), cmul(z[base + 1], float2{k01[2], k01[3]}), cmul(z[base + 2], float2{k23[0], k23[1]}), cmul(z[base + 3], float2{k23[2], k23[3]}), 0.f, o0, o1, o2, o3);
;     z[base] = o0; z[base + 1] = o1; z[base + 2] = o2; z[base + 3] = o3; }
;   __syncthreads();
	v_pk_mul_f32 v[12:13], v[226:227], v[18:19] op_sel:[1,1] op_sel_hi:[0,1]
	s_nop 0
	v_pk_fma_f32 v[26:27], v[226:227], v[18:19], v[12:13] neg_lo:[0,0,1] neg_hi:[0,0,1]
	v_pk_fma_f32 v[226:227], v[226:227], v[18:19], v[12:13] op_sel_hi:[1,0,1]
	s_nop 0
	v_mov_b32_e32 v226, v21
	v_mov_b32_e32 v27, v227
	v_pk_mul_f32 v[226:227], v[228:229], v[226:227] op_sel:[1,0] op_sel_hi:[0,0]
	s_nop 0
	v_pk_fma_f32 v[12:13], v[228:229], v[20:21], v[226:227] op_sel_hi:[1,0,1] neg_lo:[0,0,1] neg_hi:[0,0,1]
	v_pk_fma_f32 v[226:227], v[228:229], v[20:21], v[226:227] op_sel_hi:[1,0,1]
	s_waitcnt lgkmcnt(0)
	v_pk_mul_f32 v[228:229], v[222:223], v[22:23] op_sel:[1,1] op_sel_hi:[0,1]
	s_nop 0
	v_pk_fma_f32 v[18:19], v[222:223], v[22:23], v[228:229] op_sel_hi:[1,0,1] neg_lo:[0,0,1] neg_hi:[0,0,1]
	v_pk_fma_f32 v[222:223], v[222:223], v[22:23], v[228:229] op_sel_hi:[1,0,1]
	v_mov_b32_e32 v228, v25
	v_pk_mul_f32 v[228:229], v[224:225], v[228:229] op_sel:[1,0] op_sel_hi:[0,0]
	s_nop 0
	v_pk_fma_f32 v[20:21], v[224:225], v[24:25], v[228:229] op_sel_hi:[1,0,1] neg_lo:[0,0,1] neg_hi:[0,0,1]
	v_pk_fma_f32 v[224:225], v[224:225], v[24:25], v[228:229] op_sel_hi:[1,0,1]
	v_pk_mov_b32 v[228:229], v[226:227], v[12:13] op_sel:[1,0]
	s_nop 0
	v_pk_fma_f32 v[12:13], v[228:229], 0, v[12:13] op_sel_hi:[1,0,1] neg_lo:[1,0,0] neg_hi:[1,0,0]
	v_pk_fma_f32 v[226:227], v[228:229], 0, v[226:227] op_sel_hi:[1,0,1]
	s_nop 0
	v_mov_b32_e32 v13, v227
	v_pk_mov_b32 v[226:227], v[222:223], v[18:19] op_sel:[1,0]
	s_nop 0
	v_pk_fma_f32 v[228:229], v[226:227], 0, v[18:19] op_sel_hi:[1,0,1] neg_lo:[1,0,0] neg_hi:[1,0,0]
	v_pk_fma_f32 v[222:223], v[226:227], 0, v[222:223] op_sel_hi:[1,0,1]
	s_nop 0
	v_mov_b32_e32 v229, v223
	v_pk_mov_b32 v[222:223], v[224:225], v[20:21] op_sel:[1,0]
	v_pk_add_f32 v[18:19], v[26:27], v[228:229]
	v_pk_fma_f32 v[226:227], v[222:223], 0, v[20:21] op_sel_hi:[1,0,1] neg_lo:[1,0,0] neg_hi:[1,0,0]
	v_pk_fma_f32 v[222:223], v[222:223], 0, v[224:225] op_sel_hi:[1,0,1]
	v_pk_add_f32 v[224:225], v[26:27], v[228:229] neg_lo:[0,1] neg_hi:[0,1]
	v_mov_b32_e32 v227, v223
	v_pk_add_f32 v[20:21], v[12:13], v[226:227]
	v_pk_add_f32 v[226:227], v[12:13], v[226:227] neg_lo:[0,1] neg_hi:[0,1]
	v_pk_add_f32 v[222:223], v[18:19], v[20:21]
	v_pk_add_f32 v[228:229], v[224:225], v[226:227] op_sel:[0,1] op_sel_hi:[1,0] neg_lo:[0,1] neg_hi:[0,1]
	v_pk_add_f32 v[226:227], v[224:225], v[226:227] op_sel:[0,1] op_sel_hi:[1,0]
	v_mov_b32_e32 v224, v228
	v_mov_b32_e32 v225, v227
	ds_write_b128 v17, v[222:225]
	v_add_u32_e32 v222, 0x200, v3
	v_pk_add_f32 v[224:225], v[18:19], v[20:21] neg_lo:[0,1] neg_hi:[0,1]
	v_mov_b32_e32 v227, v229
	v_mov_b32_e32 v3, v222
	ds_write_b128 v17, v[224:227] offset:16
	s_nop 0
	v_lshlrev_b32_e32 v219, 3, v218
	v_and_b32_e32 v220, 0xffe0, v219
	global_load_dwordx4 v[222:225], v220, s[80:81] offset:16
	global_load_dwordx4 v[226:229], v220, s[80:81]
	v_add_u32_e32 v218, 0x800, v218
	v_ashrrev_i32_e32 v4, 31, v3
	v_lshrrev_b32_e32 v4, 21, v4
	v_add_lshl_u32 v4, v3, v4, 5
	v_and_b32_e32 v12, 0xffff0000, v4
	v_lshlrev_b32_e32 v4, 3, v2
	v_and_b32_e32 v13, 0xffe0, v4
	s_nop 0
	v_add3_u32 v17, 16, v12, v13
	ds_read_b128 v[18:21], v17
	ds_read_b128 v[22:25], v17 offset:16
	s_nop 0
	v_add_u32_e32 v2, 0x800, v2
	s_nop 0
	s_waitcnt vmcnt(4) lgkmcnt(1)
	v_pk_mul_f32 v[12:13], v[234:235], v[18:19] op_sel:[1,1] op_sel_hi:[0,1]
	s_nop 0
	v_pk_fma_f32 v[26:27], v[234:235], v[18:19], v[12:13] neg_lo:[0,0,1] neg_hi:[0,0,1]
	v_pk_fma_f32 v[234:235], v[234:235], v[18:19], v[12:13] op_sel_hi:[1,0,1]
	s_nop 0
	v_mov_b32_e32 v234, v21
	v_mov_b32_e32 v27, v235
	v_pk_mul_f32 v[234:235], v[236:237], v[234:235] op_sel:[1,0] op_sel_hi:[0,0]
	s_nop 0
	v_pk_fma_f32 v[12:13], v[236:237], v[20:21], v[234:235] op_sel_hi:[1,0,1] neg_lo:[0,0,1] neg_hi:[0,0,1]
	v_pk_fma_f32 v[234:235], v[236:237], v[20:21], v[234:235] op_sel_hi:[1,0,1]
	s_waitcnt lgkmcnt(0)
	v_pk_mul_f32 v[236:237], v[230:231], v[22:23] op_sel:[1,1] op_sel_hi:[0,1]
	s_nop 0
	v_pk_fma_f32 v[18:19], v[230:231], v[22:23], v[236:237] op_sel_hi:[1,0,1] neg_lo:[0,0,1] neg_hi:[0,0,1]
	v_pk_fma_f32 v[230:231], v[230:231], v[22:23], v[236:237] op_sel_hi:[1,0,1]
	v_mov_b32_e32 v236, v25
	v_pk_mul_f32 v[236:237], v[232:233], v[236:237] op_sel:[1,0] op_sel_hi:[0,0]
	s_nop 0
	v_pk_fma_f32 v[20:21], v[232:233], v[24:25], v[236:237] op_sel_hi:[1,0,1] neg_lo:[0,0,1] neg_hi:[0,0,1]
	v_pk_fma_f32 v[232:233], v[232:233], v[24:25], v[236:237] op_sel_hi:[1,0,1]
	v_pk_mov_b32 v[236:237], v[234:235], v[12:13] op_sel:[1,0]
	s_nop 0
	v_pk_fma_f32 v[12:13], v[236:237], 0, v[12:13] op_sel_hi:[1,0,1] neg_lo:[1,0,0] neg_hi:[1,0,0]
	v_pk_fma_f32 v[234:235], v[236:237], 0, v[234:235] op_sel_hi:[1,0,1]
	s_nop 0
	v_mov_b32_e32 v13, v235
	v_pk_mov_b32 v[234:235], v[230:231], v[18:19] op_sel:[1,0]
	s_nop 0
	v_pk_fma_f32 v[236:237], v[234:235], 0, v[18:19] op_sel_hi:[1,0,1] neg_lo:[1,0,0] neg_hi:[1,0,0]
	v_pk_fma_f32 v[230:231], v[234:235], 0, v[230:231] op_sel_hi:[1,0,1]
	s_nop 0
	v_mov_b32_e32 v237, v231
	v_pk_mov_b32 v[230:231], v[232:233], v[20:21] op_sel:[1,0]
	v_pk_add_f32 v[18:19], v[26:27], v[236:237]
	v_pk_fma_f32 v[234:235], v[230:231], 0, v[20:21] op_sel_hi:[1,0,1] neg_lo:[1,0,0] neg_hi:[1,0,0]
	v_pk_fma_f32 v[230:231], v[230:231], 0, v[232:233] op_sel_hi:[1,0,1]
	v_pk_add_f32 v[232:233], v[26:27], v[236:237] neg_lo:[0,1] neg_hi:[0,1]
	v_mov_b32_e32 v235, v231
	v_pk_add_f32 v[20:21], v[12:13], v[234:235]
	v_pk_add_f32 v[234:235], v[12:13], v[234:235] neg_lo:[0,1] neg_hi:[0,1]
	v_pk_add_f32 v[230:231], v[18:19], v[20:21]
	v_pk_add_f32 v[236:237], v[232:233], v[234:235] op_sel:[0,1] op_sel_hi:[1,0] neg_lo:[0,1] neg_hi:[0,1]
	v_pk_add_f32 v[234:235], v[232:233], v[234:235] op_sel:[0,1] op_sel_hi:[1,0]
	v_mov_b32_e32 v232, v236
	v_mov_b32_e32 v233, v235
	ds_write_b128 v17, v[230:233]
	v_add_u32_e32 v230, 0x200, v3
	v_pk_add_f32 v[232:233], v[18:19], v[20:21] neg_lo:[0,1] neg_hi:[0,1]
	v_mov_b32_e32 v235, v237
	v_mov_b32_e32 v3, v230
	ds_write_b128 v17, v[232:235] offset:16
	s_nop 0
	v_lshlrev_b32_e32 v219, 3, v218
	v_and_b32_e32 v220, 0xffe0, v219
	global_load_dwordx4 v[230:233], v220, s[80:81] offset:16
	global_load_dwordx4 v[234:237], v220, s[80:81]
	v_add_u32_e32 v218, 0x800, v218
	v_ashrrev_i32_e32 v4, 31, v3
	v_lshrrev_b32_e32 v4, 21, v4
	v_add_lshl_u32 v4, v3, v4, 5
	v_and_b32_e32 v12, 0xffff0000, v4
	v_lshlrev_b32_e32 v4, 3, v2
	v_and_b32_e32 v13, 0xffe0, v4
	s_nop 0
	v_add3_u32 v17, 16, v12, v13
	ds_read_b128 v[18:21], v17
	ds_read_b128 v[22:25], v17 offset:16
	s_nop 0
	v_add_u32_e32 v2, 0x800, v2
	s_nop 0
	s_waitcnt vmcnt(4) lgkmcnt(1)
; DI float2 twid(float r) { return float2{__builtin_amdgcn_cosf(r), -__builtin_amdgcn_sinf(r)}; }
; DI void bfly_inv(float2 s0, float2 s1, float2 s2, float2 s3, float r, float2& o0, float2& o1, float2& o2, float2& o3) {
;   float2 w1 = twid(r), w2 = cmul(w1, w1), w3 = cmul(w2, w1);
;   float2 c0 = s0, c1 = cmulc(s1, w1), c2 = cmulc(s2, w2), c3 = cmulc(s3, w3);
;   float2 t0 = {c0.x + c2.x, c0.y + c2.y}, t1 = {c0.x - c2.x, c0.y - c2.y}, t2 = {c1.x + c3.x, c1.y + c3.y}, t3 = {c1.x - c3.x, c1.y - c3.y};
;   o0 = float2{t0.x + t2.x, t0.y + t2.y}; o2 = float2{t0.x - t2.x, t0.y - t2.y}; o1 = float2{t1.x - t3.y, t1.y + t3.x}; o3 = float2{t1.x + t3.y, t1.y - t3.x};
; }
;   for (int bb = tid; bb < NBT * (N / 4); bb += NTHR) { const int b = bb & (N / 4 - 1); float2* z = z0 + (bb / (N / 4)) * N; const int base = b * 4; f32x4 k01 = *(const f32x4*)(kh + base), k23 = *(const f32x4*)(kh + base + 2); float2 o0, o1, o2, o3;
;     bfly_inv(cmul(z[base], float2{k01[0], k01[1]}), cmul(z[base + 1], float2{k01[2], k01[3]}), cmul(z[base + 2], float2{k23[0], k23[1]}), cmul(z[base + 3], float2{k23[2], k23[3]}), 0.f, o0, o1, o2, o3);
;     z[base] = o0; z[base + 1] = o1; z[base + 2] = o2; z[base + 3] = o3; }
;   __syncthreads();
	v_pk_mul_f32 v[12:13], v[246:247], v[18:19] op_sel:[1,1] op_sel_hi:[0,1]
	s_nop 0
	v_pk_fma_f32 v[26:27], v[246:247], v[18:19], v[12:13] neg_lo:[0,0,1] neg_hi:[0,0,1]
	v_pk_fma_f32 v[246:247], v[246:247], v[18:19], v[12:13] op_sel_hi:[1,0,1]
	s_nop 0
	v_mov_b32_e32 v246, v21
	v_mov_b32_e32 v27, v247
	v_pk_mul_f32 v[246:247], v[248:249], v[246:247] op_sel:[1,0] op_sel_hi:[0,0]
	s_nop 0
	v_pk_fma_f32 v[12:13], v[248:249], v[20:21], v[246:247] op_sel_hi:[1,0,1] neg_lo:[0,0,1] neg_hi:[0,0,1]
	v_pk_fma_f32 v[246:247], v[248:249], v[20:21], v[246:247] op_sel_hi:[1,0,1]
	s_waitcnt lgkmcnt(0)
	v_pk_mul_f32 v[248:249], v[242:243], v[22:23] op_sel:[1,1] op_sel_hi:[0,1]
	s_nop 0
	v_pk_fma_f32 v[18:19], v[242:243], v[22:23], v[248:249] op_sel_hi:[1,0,1] neg_lo:[0,0,1] neg_hi:[0,0,1]
	v_pk_fma_f32 v[242:243], v[242:243], v[22:23], v[248:249] op_sel_hi:[1,0,1]
	v_mov_b32_e32 v248, v25
	v_pk_mul_f32 v[248:249], v[244:245], v[248:249] op_sel:[1,0] op_sel_hi:[0,0]
	s_nop 0
	v_pk_fma_f32 v[20:21], v[244:245], v[24:25], v[248:249] op_sel_hi:[1,0,1] neg_lo:[0,0,1] neg_hi:[0,0,1]
	v_pk_fma_f32 v[244:245], v[244:245], v[24:25], v[248:249] op_sel_hi:[1,0,1]
	v_pk_mov_b32 v[248:249], v[246:247], v[12:13] op_sel:[1,0]
	s_nop 0
	v_pk_fma_f32 v[12:13], v[248:249], 0, v[12:13] op_sel_hi:[1,0,1] neg_lo:[1,0,0] neg_hi:[1,0,0]
	v_pk_fma_f32 v[246:247], v[248:249], 0, v[246:247] op_sel_hi:[1,0,1]
	s_nop 0
	v_mov_b32_e32 v13, v247
	v_pk_mov_b32 v[246:247], v[242:243], v[18:19] op_sel:[1,0]
	s_nop 0
	v_pk_fma_f32 v[248:249], v[246:247], 0, v[18:19] op_sel_hi:[1,0,1] neg_lo:[1,0,0] neg_hi:[1,0,0]
	v_pk_fma_f32 v[242:243], v[246:247], 0, v[242:243] op_sel_hi:[1,0,1]
	s_nop 0
	v_mov_b32_e32 v249, v243
	v_pk_mov_b32 v[242:243], v[244:245], v[20:21] op_sel:[1,0]
	v_pk_add_f32 v[18:19], v[26:27], v[248:249]
	v_pk_fma_f32 v[246:247], v[242:243], 0, v[20:21] op_sel_hi:[1,0,1] neg_lo:[1,0,0] neg_hi:[1,0,0]
	v_pk_fma_f32 v[242:243], v[242:243], 0, v[244:245] op_sel_hi:[1,0,1]
	v_pk_add_f32 v[244:245], v[26:27], v[248:249] neg_lo:[0,1] neg_hi:[0,1]
	v_mov_b32_e32 v247, v243
	v_pk_add_f32 v[20:21], v[12:13], v[246:247]
	v_pk_add_f32 v[246:247], v[12:13], v[246:247] neg_lo:[0,1] neg_hi:[0,1]
	v_pk_add_f32 v[242:243], v[18:19], v[20:21]
	v_pk_add_f32 v[248:249], v[244:245], v[246:247] op_sel:[0,1] op_sel_hi:[1,0] neg_lo:[0,1] neg_hi:[0,1]
	v_pk_add_f32 v[246:247], v[244:245], v[246:247] op_sel:[0,1] op_sel_hi:[1,0]
	v_mov_b32_e32 v244, v248
	v_mov_b32_e32 v245, v247
	ds_write_b128 v17, v[242:245]
	v_add_u32_e32 v242, 0x200, v3
	v_pk_add_f32 v[244:245], v[18:19], v[20:21] neg_lo:[0,1] neg_hi:[0,1]
	v_mov_b32_e32 v247, v249
	v_mov_b32_e32 v3, v242
	ds_write_b128 v17, v[244:247] offset:16
	s_nop 0
	v_ashrrev_i32_e32 v4, 31, v3
	v_lshrrev_b32_e32 v4, 21, v4
	v_add_lshl_u32 v4, v3, v4, 5
	v_and_b32_e32 v12, 0xffff0000, v4
	v_lshlrev_b32_e32 v4, 3, v2
	v_and_b32_e32 v13, 0xffe0, v4
	s_nop 0
	v_add3_u32 v17, 16, v12, v13
	ds_read_b128 v[18:21], v17
	ds_read_b128 v[22:25], v17 offset:16
	s_nop 0
	v_add_u32_e32 v2, 0x800, v2
	s_nop 0
	s_waitcnt vmcnt(2) lgkmcnt(1)
	v_pk_mul_f32 v[12:13], v[226:227], v[18:19] op_sel:[1,1] op_sel_hi:[0,1]
	s_nop 0
	v_pk_fma_f32 v[26:27], v[226:227], v[18:19], v[12:13] neg_lo:[0,0,1] neg_hi:[0,0,1]
	v_pk_fma_f32 v[226:227], v[226:227], v[18:19], v[12:13] op_sel_hi:[1,0,1]
	s_nop 0
	v_mov_b32_e32 v226, v21
	v_mov_b32_e32 v27, v227
	v_pk_mul_f32 v[226:227], v[228:229], v[226:227] op_sel:[1,0] op_sel_hi:[0,0]
	s_nop 0
	v_pk_fma_f32 v[12:13], v[228:229], v[20:21], v[226:227] op_sel_hi:[1,0,1] neg_lo:[0,0,1] neg_hi:[0,0,1]
	v_pk_fma_f32 v[226:227], v[228:229], v[20:21], v[226:227] op_sel_hi:[1,0,1]
	s_waitcnt lgkmcnt(0)
; DI float2 twid(float r) { return float2{__builtin_amdgcn_cosf(r), -__builtin_amdgcn_sinf(r)}; }
; DI void bfly_inv(float2 s0, float2 s1, float2 s2, float2 s3, float r, float2& o0, float2& o1, float2& o2, float2& o3) {
;   float2 w1 = twid(r), w2 = cmul(w1, w1), w3 = cmul(w2, w1);
;   float2 c0 = s0, c1 = cmulc(s1, w1), c2 = cmulc(s2, w2), c3 = cmulc(s3, w3);
;   float2 t0 = {c0.x + c2.x, c0.y + c2.y}, t1 = {c0.x - c2.x, c0.y - c2.y}, t2 = {c1.x + c3.x, c1.y + c3.y}, t3 = {c1.x - c3.x, c1.y - c3.y};
;   o0 = float2{t0.x + t2.x, t0.y + t2.y}; o2 = float2{t0.x - t2.x, t0.y - t2.y}; o1 = float2{t1.x - t3.y, t1.y + t3.x}; o3 = float2{t1.x + t3.y, t1.y - t3.x};
; }
;   for (int bb = tid; bb < NBT * (N / 4); bb += NTHR) { const int b = bb & (N / 4 - 1); float2* z = z0 + (bb / (N / 4)) * N; const int base = b * 4; f32x4 k01 = *(const f32x4*)(kh + base), k23 = *(const f32x4*)(kh + base + 2); float2 o0, o1, o2, o3;
;     bfly_inv(cmul(z[base], float2{k01[0], k01[1]}), cmul(z[base + 1], float2{k01[2], k01[3]}), cmul(z[base + 2], float2{k23[0], k23[1]}), cmul(z[base + 3], float2{k23[2], k23[3]}), 0.f, o0, o1, o2, o3);
;     z[base] = o0; z[base + 1] = o1; z[base + 2] = o2; z[base + 3] = o3; }
;   __syncthreads();
	v_pk_mul_f32 v[228:229], v[222:223], v[22:23] op_sel:[1,1] op_sel_hi:[0,1]
	s_nop 0
	v_pk_fma_f32 v[18:19], v[222:223], v[22:23], v[228:229] op_sel_hi:[1,0,1] neg_lo:[0,0,1] neg_hi:[0,0,1]
	v_pk_fma_f32 v[222:223], v[222:223], v[22:23], v[228:229] op_sel_hi:[1,0,1]
	v_mov_b32_e32 v228, v25
	v_pk_mul_f32 v[228:229], v[224:225], v[228:229] op_sel:[1,0] op_sel_hi:[0,0]
	s_nop 0
	v_pk_fma_f32 v[20:21], v[224:225], v[24:25], v[228:229] op_sel_hi:[1,0,1] neg_lo:[0,0,1] neg_hi:[0,0,1]
	v_pk_fma_f32 v[224:225], v[224:225], v[24:25], v[228:229] op_sel_hi:[1,0,1]
	v_pk_mov_b32 v[228:229], v[226:227], v[12:13] op_sel:[1,0]
	s_nop 0
	v_pk_fma_f32 v[12:13], v[228:229], 0, v[12:13] op_sel_hi:[1,0,1] neg_lo:[1,0,0] neg_hi:[1,0,0]
	v_pk_fma_f32 v[226:227], v[228:229], 0, v[226:227] op_sel_hi:[1,0,1]
	s_nop 0
	v_mov_b32_e32 v13, v227
	v_pk_mov_b32 v[226:227], v[222:223], v[18:19] op_sel:[1,0]
	s_nop 0
	v_pk_fma_f32 v[228:229], v[226:227], 0, v[18:19] op_sel_hi:[1,0,1] neg_lo:[1,0,0] neg_hi:[1,0,0]
	v_pk_fma_f32 v[222:223], v[226:227], 0, v[222:223] op_sel_hi:[1,0,1]
	s_nop 0
	v_mov_b32_e32 v229, v223
	v_pk_mov_b32 v[222:223], v[224:225], v[20:21] op_sel:[1,0]
	v_pk_add_f32 v[18:19], v[26:27], v[228:229]
	v_pk_fma_f32 v[226:227], v[222:223], 0, v[20:21] op_sel_hi:[1,0,1] neg_lo:[1,0,0] neg_hi:[1,0,0]
	v_pk_fma_f32 v[222:223], v[222:223], 0, v[224:225] op_sel_hi:[1,0,1]
	v_pk_add_f32 v[224:225], v[26:27], v[228:229] neg_lo:[0,1] neg_hi:[0,1]
	v_mov_b32_e32 v227, v223
	v_pk_add_f32 v[20:21], v[12:13], v[226:227]
	v_pk_add_f32 v[226:227], v[12:13], v[226:227] neg_lo:[0,1] neg_hi:[0,1]
	v_pk_add_f32 v[222:223], v[18:19], v[20:21]
	v_pk_add_f32 v[228:229], v[224:225], v[226:227] op_sel:[0,1] op_sel_hi:[1,0] neg_lo:[0,1] neg_hi:[0,1]
	v_pk_add_f32 v[226:227], v[224:225], v[226:227] op_sel:[0,1] op_sel_hi:[1,0]
	v_mov_b32_e32 v224, v228
	v_mov_b32_e32 v225, v227
	ds_write_b128 v17, v[222:225]
	v_add_u32_e32 v222, 0x200, v3
	v_pk_add_f32 v[224:225], v[18:19], v[20:21] neg_lo:[0,1] neg_hi:[0,1]
	v_mov_b32_e32 v227, v229
	v_mov_b32_e32 v3, v222
	ds_write_b128 v17, v[224:227] offset:16
	s_nop 0
	v_ashrrev_i32_e32 v4, 31, v3
	v_lshrrev_b32_e32 v4, 21, v4
	v_add_lshl_u32 v4, v3, v4, 5
	v_and_b32_e32 v12, 0xffff0000, v4
	v_lshlrev_b32_e32 v4, 3, v2
	v_and_b32_e32 v13, 0xffe0, v4
	s_nop 0
	v_add3_u32 v17, 16, v12, v13
	ds_read_b128 v[18:21], v17
	ds_read_b128 v[22:25], v17 offset:16
	s_nop 0
	v_add_u32_e32 v2, 0x800, v2
	s_nop 0
	s_waitcnt vmcnt(0) lgkmcnt(1)
	v_pk_mul_f32 v[12:13], v[234:235], v[18:19] op_sel:[1,1] op_sel_hi:[0,1]
	s_nop 0
	v_pk_fma_f32 v[26:27], v[234:235], v[18:19], v[12:13] neg_lo:[0,0,1] neg_hi:[0,0,1]
	v_pk_fma_f32 v[234:235], v[234:235], v[18:19], v[12:13] op_sel_hi:[1,0,1]
	s_nop 0
	v_mov_b32_e32 v234, v21
	v_mov_b32_e32 v27, v235
	v_pk_mul_f32 v[234:235], v[236:237], v[234:235] op_sel:[1,0] op_sel_hi:[0,0]
	s_nop 0
	v_pk_fma_f32 v[12:13], v[236:237], v[20:21], v[234:235] op_sel_hi:[1,0,1] neg_lo:[0,0,1] neg_hi:[0,0,1]
	v_pk_fma_f32 v[234:235], v[236:237], v[20:21], v[234:235] op_sel_hi:[1,0,1]
	s_waitcnt lgkmcnt(0)
	v_pk_mul_f32 v[236:237], v[230:231], v[22:23] op_sel:[1,1] op_sel_hi:[0,1]
	s_nop 0
	v_pk_fma_f32 v[18:19], v[230:231], v[22:23], v[236:237] op_sel_hi:[1,0,1] neg_lo:[0,0,1] neg_hi:[0,0,1]
	v_pk_fma_f32 v[230:231], v[230:231], v[22:23], v[236:237] op_sel_hi:[1,0,1]
	v_mov_b32_e32 v236, v25
	v_pk_mul_f32 v[236:237], v[232:233], v[236:237] op_sel:[1,0] op_sel_hi:[0,0]
	s_nop 0
	v_pk_fma_f32 v[20:21], v[232:233], v[24:25], v[236:237] op_sel_hi:[1,0,1] neg_lo:[0,0,1] neg_hi:[0,0,1]
	v_pk_fma_f32 v[232:233], v[232:233], v[24:25], v[236:237] op_sel_hi:[1,0,1]
	v_pk_mov_b32 v[236:237], v[234:235], v[12:13] op_sel:[1,0]
	s_nop 0
	v_pk_fma_f32 v[12:13], v[236:237], 0, v[12:13] op_sel_hi:[1,0,1] neg_lo:[1,0,0] neg_hi:[1,0,0]
	v_pk_fma_f32 v[234:235], v[236:237], 0, v[234:235] op_sel_hi:[1,0,1]
	s_nop 0
	v_mov_b32_e32 v13, v235
	v_pk_mov_b32 v[234:235], v[230:231], v[18:19] op_sel:[1,0]
	s_nop 0
	v_pk_fma_f32 v[236:237], v[234:235], 0, v[18:19] op_sel_hi:[1,0,1] neg_lo:[1,0,0] neg_hi:[1,0,0]
	v_pk_fma_f32 v[230:231], v[234:235], 0, v[230:231] op_sel_hi:[1,0,1]
	s_nop 0
	v_mov_b32_e32 v237, v231
	v_pk_mov_b32 v[230:231], v[232:233], v[20:21] op_sel:[1,0]
	v_pk_add_f32 v[18:19], v[26:27], v[236:237]
	v_pk_fma_f32 v[234:235], v[230:231], 0, v[20:21] op_sel_hi:[1,0,1] neg_lo:[1,0,0] neg_hi:[1,0,0]
	v_pk_fma_f32 v[230:231], v[230:231], 0, v[232:233] op_sel_hi:[1,0,1]
	v_pk_add_f32 v[232:233], v[26:27], v[236:237] neg_lo:[0,1] neg_hi:[0,1]
	v_mov_b32_e32 v235, v231
	v_pk_add_f32 v[20:21], v[12:13], v[234:235]
	v_pk_add_f32 v[234:235], v[12:13], v[234:235] neg_lo:[0,1] neg_hi:[0,1]
	v_pk_add_f32 v[230:231], v[18:19], v[20:21]
	v_pk_add_f32 v[236:237], v[232:233], v[234:235] op_sel:[0,1] op_sel_hi:[1,0] neg_lo:[0,1] neg_hi:[0,1]
	v_pk_add_f32 v[234:235], v[232:233], v[234:235] op_sel:[0,1] op_sel_hi:[1,0]
	v_mov_b32_e32 v232, v236
	v_mov_b32_e32 v233, v235
	ds_write_b128 v17, v[230:233]
	v_add_u32_e32 v230, 0x200, v3
	v_pk_add_f32 v[232:233], v[18:19], v[20:21] neg_lo:[0,1] neg_hi:[0,1]
	v_mov_b32_e32 v235, v237
	v_mov_b32_e32 v3, v230
	ds_write_b128 v17, v[232:235] offset:16
	s_nop 0
	s_mov_b64 s[84:85], exec

; DI float2 twid(float r) { return float2{__builtin_amdgcn_cosf(r), -__builtin_amdgcn_sinf(r)}; }
; DI void bfly_inv(float2 s0, float2 s1, float2 s2, float2 s3, float r, float2& o0, float2& o1, float2& o2, float2& o3) {
;   float2 w1 = twid(r), w2 = cmul(w1, w1), w3 = cmul(w2, w1);
;   float2 c0 = s0, c1 = cmulc(s1, w1), c2 = cmulc(s2, w2), c3 = cmulc(s3, w3);
;   float2 t0 = {c0.x + c2.x, c0.y + c2.y}, t1 = {c0.x - c2.x, c0.y - c2.y}, t2 = {c1.x + c3.x, c1.y + c3.y}, t3 = {c1.x - c3.x, c1.y - c3.y};
;   o0 = float2{t0.x + t2.x, t0.y + t2.y}; o2 = float2{t0.x - t2.x, t0.y - t2.y}; o1 = float2{t1.x - t3.y, t1.y + t3.x}; o3 = float2{t1.x + t3.y, t1.y - t3.x};
; }
;   for (int bb = tid; bb < NBT * (N / 4); bb += NTHR) { const int b = bb & (N / 4 - 1); float2* z = z0 + (bb / (N / 4)) * N; const int base = b * 4; f32x4 k01 = *(const f32x4*)(kh + base), k23 = *(const f32x4*)(kh + base + 2); float2 o0, o1, o2, o3;
;     bfly_inv(cmul(z[base], float2{k01[0], k01[1]}), cmul(z[base + 1], float2{k01[2], k01[3]}), cmul(z[base + 2], float2{k23[0], k23[1]}), cmul(z[base + 3], float2{k23[2], k23[3]}), 0.f, o0, o1, o2, o3);
;     z[base] = o0; z[base + 1] = o1; z[base + 2] = o2; z[base + 3] = o3; }
;   __syncthreads();
.LBB0_1644:
	v_mov_b32_e32 v218, v4
	v_lshlrev_b32_e32 v219, 3, v218
	v_and_b32_e32 v220, 0x1ffe0, v219
	global_load_dwordx4 v[222:225], v220, s[80:81] offset:16
	global_load_dwordx4 v[226:229], v220, s[80:81]
	v_add_u32_e32 v218, 0x800, v218
	v_lshlrev_b32_e32 v219, 3, v218
	v_and_b32_e32 v220, 0x1ffe0, v219
	global_load_dwordx4 v[230:233], v220, s[80:81] offset:16
	global_load_dwordx4 v[234:237], v220, s[80:81]
	v_add_u32_e32 v218, 0x800, v218
	v_lshlrev_b32_e32 v219, 3, v218
	v_and_b32_e32 v220, 0x1ffe0, v219
	global_load_dwordx4 v[242:245], v220, s[80:81] offset:16
	global_load_dwordx4 v[246:249], v220, s[80:81]
	v_add_u32_e32 v218, 0x800, v218
	v_ashrrev_i32_e32 v6, 31, v5
	v_lshrrev_b32_e32 v6, 20, v6
	v_add_lshl_u32 v6, v5, v6, 5
	v_and_b32_e32 v14, 0xfffe0000, v6
	v_lshlrev_b32_e32 v6, 3, v4
	v_and_b32_e32 v15, 0x1ffe0, v6
	s_nop 0
	v_add3_u32 v19, 16, v14, v15
	ds_read_b128 v[20:23], v19
	ds_read_b128 v[24:27], v19 offset:16
	s_nop 0
	v_add_u32_e32 v4, 0x800, v4
	s_nop 0
	s_waitcnt vmcnt(4) lgkmcnt(1)
	v_pk_mul_f32 v[14:15], v[226:227], v[20:21] op_sel:[1,1] op_sel_hi:[0,1]
	s_nop 0
	v_pk_fma_f32 v[28:29], v[226:227], v[20:21], v[14:15] neg_lo:[0,0,1] neg_hi:[0,0,1]
	v_pk_fma_f32 v[226:227], v[226:227], v[20:21], v[14:15] op_sel_hi:[1,0,1]
	s_nop 0
	v_mov_b32_e32 v226, v23
	v_mov_b32_e32 v29, v227
	v_pk_mul_f32 v[226:227], v[228:229], v[226:227] op_sel:[1,0] op_sel_hi:[0,0]
	s_nop 0
	v_pk_fma_f32 v[14:15], v[228:229], v[22:23], v[226:227] op_sel_hi:[1,0,1] neg_lo:[0,0,1] neg_hi:[0,0,1]
	v_pk_fma_f32 v[226:227], v[228:229], v[22:23], v[226:227] op_sel_hi:[1,0,1]
	s_waitcnt lgkmcnt(0)
	v_pk_mul_f32 v[228:229], v[222:223], v[24:25] op_sel:[1,1] op_sel_hi:[0,1]
	s_nop 0
	v_pk_fma_f32 v[20:21], v[222:223], v[24:25], v[228:229] op_sel_hi:[1,0,1] neg_lo:[0,0,1] neg_hi:[0,0,1]
	v_pk_fma_f32 v[222:223], v[222:223], v[24:25], v[228:229] op_sel_hi:[1,0,1]
	v_mov_b32_e32 v228, v27
	v_pk_mul_f32 v[228:229], v[224:225], v[228:229] op_sel:[1,0] op_sel_hi:[0,0]
	s_nop 0
	v_pk_fma_f32 v[22:23], v[224:225], v[26:27], v[228:229] op_sel_hi:[1,0,1] neg_lo:[0,0,1] neg_hi:[0,0,1]
	v_pk_fma_f32 v[224:225], v[224:225], v[26:27], v[228:229] op_sel_hi:[1,0,1]
	v_pk_mov_b32 v[228:229], v[226:227], v[14:15] op_sel:[1,0]
	s_nop 0
	v_pk_fma_f32 v[14:15], v[228:229], 0, v[14:15] op_sel_hi:[1,0,1] neg_lo:[1,0,0] neg_hi:[1,0,0]
	v_pk_fma_f32 v[226:227], v[228:229], 0, v[226:227] op_sel_hi:[1,0,1]
	s_nop 0
	v_mov_b32_e32 v15, v227
	v_pk_mov_b32 v[226:227], v[222:223], v[20:21] op_sel:[1,0]
	s_nop 0
	v_pk_fma_f32 v[228:229], v[226:227], 0, v[20:21] op_sel_hi:[1,0,1] neg_lo:[1,0,0] neg_hi:[1,0,0]
	v_pk_fma_f32 v[222:223], v[226:227], 0, v[222:223] op_sel_hi:[1,0,1]
	s_nop 0
	v_mov_b32_e32 v229, v223
	v_pk_mov_b32 v[222:223], v[224:225], v[22:23] op_sel:[1,0]
	v_pk_add_f32 v[20:21], v[28:29], v[228:229]
	v_pk_fma_f32 v[226:227], v[222:223], 0, v[22:23] op_sel_hi:[1,0,1] neg_lo:[1,0,0] neg_hi:[1,0,0]
	v_pk_fma_f32 v[222:223], v[222:223], 0, v[224:225] op_sel_hi:[1,0,1]
	v_pk_add_f32 v[224:225], v[28:29], v[228:229] neg_lo:[0,1] neg_hi:[0,1]
	v_mov_b32_e32 v227, v223
	v_pk_add_f32 v[22:23], v[14:15], v[226:227]
	v_pk_add_f32 v[226:227], v[14:15], v[226:227] neg_lo:[0,1] neg_hi:[0,1]
	v_pk_add_f32 v[222:223], v[20:21], v[22:23]
	v_pk_add_f32 v[228:229], v[224:225], v[226:227] op_sel:[0,1] op_sel_hi:[1,0] neg_lo:[0,1] neg_hi:[0,1]
	v_pk_add_f32 v[226:227], v[224:225], v[226:227] op_sel:[0,1] op_sel_hi:[1,0]
	v_mov_b32_e32 v224, v228
	v_mov_b32_e32 v225, v227
	ds_write_b128 v19, v[222:225]
	v_add_u32_e32 v222, 0x200, v5
	v_pk_add_f32 v[224:225], v[20:21], v[22:23] neg_lo:[0,1] neg_hi:[0,1]
	v_mov_b32_e32 v227, v229
	v_mov_b32_e32 v5, v222
	ds_write_b128 v19, v[224:227] offset:16
	s_nop 0
	v_lshlrev_b32_e32 v219, 3, v218
	v_and_b32_e32 v220, 0x1ffe0, v219
	global_load_dwordx4 v[222:225], v220, s[80:81] offset:16
	global_load_dwordx4 v[226:229], v220, s[80:81]
	v_add_u32_e32 v218, 0x800, v218
	v_ashrrev_i32_e32 v6, 31, v5
	v_lshrrev_b32_e32 v6, 20, v6
	v_add_lshl_u32 v6, v5, v6, 5
	v_and_b32_e32 v14, 0xfffe0000, v6
	v_lshlrev_b32_e32 v6, 3, v4
	v_and_b32_e32 v15, 0x1ffe0, v6
	s_nop 0
	v_add3_u32 v19, 16, v14, v15
	ds_read_b128 v[20:23], v19
	ds_read_b128 v[24:27], v19 offset:16
	s_nop 0
	v_add_u32_e32 v4, 0x800, v4
	s_nop 0
	s_waitcnt vmcnt(4) lgkmcnt(1)
	v_pk_mul_f32 v[14:15], v[234:235], v[20:21] op_sel:[1,1] op_sel_hi:[0,1]
	s_nop 0
	v_pk_fma_f32 v[28:29], v[234:235], v[20:21], v[14:15] neg_lo:[0,0,1] neg_hi:[0,0,1]
	v_pk_fma_f32 v[234:235], v[234:235], v[20:21], v[14:15] op_sel_hi:[1,0,1]
	s_nop 0
	v_mov_b32_e32 v234, v23
	v_mov_b32_e32 v29, v235
	v_pk_mul_f32 v[234:235], v[236:237], v[234:235] op_sel:[1,0] op_sel_hi:[0,0]
	s_nop 0
	v_pk_fma_f32 v[14:15], v[236:237], v[22:23], v[234:235] op_sel_hi:[1,0,1] neg_lo:[0,0,1] neg_hi:[0,0,1]
	v_pk_fma_f32 v[234:235], v[236:237], v[22:23], v[234:235] op_sel_hi:[1,0,1]
	s_waitcnt lgkmcnt(0)
; DI float2 twid(float r) { return float2{__builtin_amdgcn_cosf(r), -__builtin_amdgcn_sinf(r)}; }
; DI void bfly_inv(float2 s0, float2 s1, float2 s2, float2 s3, float r, float2& o0, float2& o1, float2& o2, float2& o3) {
;   float2 w1 = twid(r), w2 = cmul(w1, w1), w3 = cmul(w2, w1);
;   float2 c0 = s0, c1 = cmulc(s1, w1), c2 = cmulc(s2, w2), c3 = cmulc(s3, w3);
;   float2 t0 = {c0.x + c2.x, c0.y + c2.y}, t1 = {c0.x - c2.x, c0.y - c2.y}, t2 = {c1.x + c3.x, c1.y + c3.y}, t3 = {c1.x - c3.x, c1.y - c3.y};
;   o0 = float2{t0.x + t2.x, t0.y + t2.y}; o2 = float2{t0.x - t2.x, t0.y - t2.y}; o1 = float2{t1.x - t3.y, t1.y + t3.x}; o3 = float2{t1.x + t3.y, t1.y - t3.x};
; }
;   for (int bb = tid; bb < NBT * (N / 4); bb += NTHR) { const int b = bb & (N / 4 - 1); float2* z = z0 + (bb / (N / 4)) * N; const int base = b * 4; f32x4 k01 = *(const f32x4*)(kh + base), k23 = *(const f32x4*)(kh + base + 2); float2 o0, o1, o2, o3;
;     bfly_inv(cmul(z[base], float2{k01[0], k01[1]}), cmul(z[base + 1], float2{k01[2], k01[3]}), cmul(z[base + 2], float2{k23[0], k23[1]}), cmul(z[base + 3], float2{k23[2], k23[3]}), 0.f, o0, o1, o2, o3);
;     z[base] = o0; z[base + 1] = o1; z[base + 2] = o2; z[base + 3] = o3; }
;   __syncthreads();
	v_pk_mul_f32 v[236:237], v[230:231], v[24:25] op_sel:[1,1] op_sel_hi:[0,1]
	s_nop 0
	v_pk_fma_f32 v[20:21], v[230:231], v[24:25], v[236:237] op_sel_hi:[1,0,1] neg_lo:[0,0,1] neg_hi:[0,0,1]
	v_pk_fma_f32 v[230:231], v[230:231], v[24:25], v[236:237] op_sel_hi:[1,0,1]
	v_mov_b32_e32 v236, v27
	v_pk_mul_f32 v[236:237], v[232:233], v[236:237] op_sel:[1,0] op_sel_hi:[0,0]
	s_nop 0
	v_pk_fma_f32 v[22:23], v[232:233], v[26:27], v[236:237] op_sel_hi:[1,0,1] neg_lo:[0,0,1] neg_hi:[0,0,1]
	v_pk_fma_f32 v[232:233], v[232:233], v[26:27], v[236:237] op_sel_hi:[1,0,1]
	v_pk_mov_b32 v[236:237], v[234:235], v[14:15] op_sel:[1,0]
	s_nop 0
	v_pk_fma_f32 v[14:15], v[236:237], 0, v[14:15] op_sel_hi:[1,0,1] neg_lo:[1,0,0] neg_hi:[1,0,0]
	v_pk_fma_f32 v[234:235], v[236:237], 0, v[234:235] op_sel_hi:[1,0,1]
	s_nop 0
	v_mov_b32_e32 v15, v235
	v_pk_mov_b32 v[234:235], v[230:231], v[20:21] op_sel:[1,0]
	s_nop 0
	v_pk_fma_f32 v[236:237], v[234:235], 0, v[20:21] op_sel_hi:[1,0,1] neg_lo:[1,0,0] neg_hi:[1,0,0]
	v_pk_fma_f32 v[230:231], v[234:235], 0, v[230:231] op_sel_hi:[1,0,1]
	s_nop 0
	v_mov_b32_e32 v237, v231
	v_pk_mov_b32 v[230:231], v[232:233], v[22:23] op_sel:[1,0]
	v_pk_add_f32 v[20:21], v[28:29], v[236:237]
	v_pk_fma_f32 v[234:235], v[230:231], 0, v[22:23] op_sel_hi:[1,0,1] neg_lo:[1,0,0] neg_hi:[1,0,0]
	v_pk_fma_f32 v[230:231], v[230:231], 0, v[232:233] op_sel_hi:[1,0,1]
	v_pk_add_f32 v[232:233], v[28:29], v[236:237] neg_lo:[0,1] neg_hi:[0,1]
	v_mov_b32_e32 v235, v231
	v_pk_add_f32 v[22:23], v[14:15], v[234:235]
	v_pk_add_f32 v[234:235], v[14:15], v[234:235] neg_lo:[0,1] neg_hi:[0,1]
	v_pk_add_f32 v[230:231], v[20:21], v[22:23]
	v_pk_add_f32 v[236:237], v[232:233], v[234:235] op_sel:[0,1] op_sel_hi:[1,0] neg_lo:[0,1] neg_hi:[0,1]
	v_pk_add_f32 v[234:235], v[232:233], v[234:235] op_sel:[0,1] op_sel_hi:[1,0]
	v_mov_b32_e32 v232, v236
	v_mov_b32_e32 v233, v235
	ds_write_b128 v19, v[230:233]
	v_add_u32_e32 v230, 0x200, v5
	v_pk_add_f32 v[232:233], v[20:21], v[22:23] neg_lo:[0,1] neg_hi:[0,1]
	v_mov_b32_e32 v235, v237
	v_mov_b32_e32 v5, v230
	ds_write_b128 v19, v[232:235] offset:16
	s_nop 0
	v_lshlrev_b32_e32 v219, 3, v218
	v_and_b32_e32 v220, 0x1ffe0, v219
	global_load_dwordx4 v[230:233], v220, s[80:81] offset:16
	global_load_dwordx4 v[234:237], v220, s[80:81]
	v_add_u32_e32 v218, 0x800, v218
	v_ashrrev_i32_e32 v6, 31, v5
	v_lshrrev_b32_e32 v6, 20, v6
	v_add_lshl_u32 v6, v5, v6, 5
	v_and_b32_e32 v14, 0xfffe0000, v6
	v_lshlrev_b32_e32 v6, 3, v4
	v_and_b32_e32 v15, 0x1ffe0, v6
	s_nop 0
	v_add3_u32 v19, 16, v14, v15
	ds_read_b128 v[20:23], v19
	ds_read_b128 v[24:27], v19 offset:16
	s_nop 0
	v_add_u32_e32 v4, 0x800, v4
	s_nop 0
	s_waitcnt vmcnt(4) lgkmcnt(1)
	v_pk_mul_f32 v[14:15], v[246:247], v[20:21] op_sel:[1,1] op_sel_hi:[0,1]
	s_nop 0
	v_pk_fma_f32 v[28:29], v[246:247], v[20:21], v[14:15] neg_lo:[0,0,1] neg_hi:[0,0,1]
	v_pk_fma_f32 v[246:247], v[246:247], v[20:21], v[14:15] op_sel_hi:[1,0,1]
	s_nop 0
	v_mov_b32_e32 v246, v23
	v_mov_b32_e32 v29, v247
	v_pk_mul_f32 v[246:247], v[248:249], v[246:247] op_sel:[1,0] op_sel_hi:[0,0]
	s_nop 0
	v_pk_fma_f32 v[14:15], v[248:249], v[22:23], v[246:247] op_sel_hi:[1,0,1] neg_lo:[0,0,1] neg_hi:[0,0,1]
	v_pk_fma_f32 v[246:247], v[248:249], v[22:23], v[246:247] op_sel_hi:[1,0,1]
	s_waitcnt lgkmcnt(0)
	v_pk_mul_f32 v[248:249], v[242:243], v[24:25] op_sel:[1,1] op_sel_hi:[0,1]
	s_nop 0
	v_pk_fma_f32 v[20:21], v[242:243], v[24:25], v[248:249] op_sel_hi:[1,0,1] neg_lo:[0,0,1] neg_hi:[0,0,1]
	v_pk_fma_f32 v[242:243], v[242:243], v[24:25], v[248:249] op_sel_hi:[1,0,1]
	v_mov_b32_e32 v248, v27
	v_pk_mul_f32 v[248:249], v[244:245], v[248:249] op_sel:[1,0] op_sel_hi:[0,0]
	s_nop 0
	v_pk_fma_f32 v[22:23], v[244:245], v[26:27], v[248:249] op_sel_hi:[1,0,1] neg_lo:[0,0,1] neg_hi:[0,0,1]
	v_pk_fma_f32 v[244:245], v[244:245], v[26:27], v[248:249] op_sel_hi:[1,0,1]
	v_pk_mov_b32 v[248:249], v[246:247], v[14:15] op_sel:[1,0]
	s_nop 0
	v_pk_fma_f32 v[14:15], v[248:249], 0, v[14:15] op_sel_hi:[1,0,1] neg_lo:[1,0,0] neg_hi:[1,0,0]
	v_pk_fma_f32 v[246:247], v[248:249], 0, v[246:247] op_sel_hi:[1,0,1]
	s_nop 0
	v_mov_b32_e32 v15, v247
	v_pk_mov_b32 v[246:247], v[242:243], v[20:21] op_sel:[1,0]
	s_nop 0
	v_pk_fma_f32 v[248:249], v[246:247], 0, v[20:21] op_sel_hi:[1,0,1] neg_lo:[1,0,0] neg_hi:[1,0,0]
	v_pk_fma_f32 v[242:243], v[246:247], 0, v[242:243] op_sel_hi:[1,0,1]
	s_nop 0
	v_mov_b32_e32 v249, v243
	v_pk_mov_b32 v[242:243], v[244:245], v[22:23] op_sel:[1,0]
	v_pk_add_f32 v[20:21], v[28:29], v[248:249]
	v_pk_fma_f32 v[246:247], v[242:243], 0, v[22:23] op_sel_hi:[1,0,1] neg_lo:[1,0,0] neg_hi:[1,0,0]
	v_pk_fma_f32 v[242:243], v[242:243], 0, v[244:245] op_sel_hi:[1,0,1]
	v_pk_add_f32 v[244:245], v[28:29], v[248:249] neg_lo:[0,1] neg_hi:[0,1]
	v_mov_b32_e32 v247, v243
	v_pk_add_f32 v[22:23], v[14:15], v[246:247]
	v_pk_add_f32 v[246:247], v[14:15], v[246:247] neg_lo:[0,1] neg_hi:[0,1]
	v_pk_add_f32 v[242:243], v[20:21], v[22:23]
	v_pk_add_f32 v[248:249], v[244:245], v[246:247] op_sel:[0,1] op_sel_hi:[1,0] neg_lo:[0,1] neg_hi:[0,1]
	v_pk_add_f32 v[246:247], v[244:245], v[246:247] op_sel:[0,1] op_sel_hi:[1,0]
	v_mov_b32_e32 v244, v248
	v_mov_b32_e32 v245, v247
	ds_write_b128 v19, v[242:245]
	v_add_u32_e32 v242, 0x200, v5
	v_pk_add_f32 v[244:245], v[20:21], v[22:23] neg_lo:[0,1] neg_hi:[0,1]
	v_mov_b32_e32 v247, v249
	v_mov_b32_e32 v5, v242
	ds_write_b128 v19, v[244:247] offset:16
	s_nop 0
	v_lshlrev_b32_e32 v219, 3, v218
	v_and_b32_e32 v220, 0x1ffe0, v219
	global_load_dwordx4 v[242:245], v220, s[80:81] offset:16
	global_load_dwordx4 v[246:249], v220, s[80:81]
	v_add_u32_e32 v218, 0x800, v218
	v_ashrrev_i32_e32 v6, 31, v5
	v_lshrrev_b32_e32 v6, 20, v6
	v_add_lshl_u32 v6, v5, v6, 5
	v_and_b32_e32 v14, 0xfffe0000, v6
	v_lshlrev_b32_e32 v6, 3, v4
	v_and_b32_e32 v15, 0x1ffe0, v6
	s_nop 0
	v_add3_u32 v19, 16, v14, v15
	ds_read_b128 v[20:23], v19
	ds_read_b128 v[24:27], v19 offset:16
	s_nop 0
	v_add_u32_e32 v4, 0x800, v4
	s_nop 0
	s_waitcnt vmcnt(4) lgkmcnt(1)
; DI float2 twid(float r) { return float2{__builtin_amdgcn_cosf(r), -__builtin_amdgcn_sinf(r)}; }
; DI void bfly_inv(float2 s0, float2 s1, float2 s2, float2 s3, float r, float2& o0, float2& o1, float2& o2, float2& o3) {
;   float2 w1 = twid(r), w2 = cmul(w1, w1), w3 = cmul(w2, w1);
;   float2 c0 = s0, c1 = cmulc(s1, w1), c2 = cmulc(s2, w2), c3 = cmulc(s3, w3);
;   float2 t0 = {c0.x + c2.x, c0.y + c2.y}, t1 = {c0.x - c2.x, c0.y - c2.y}, t2 = {c1.x + c3.x, c1.y + c3.y}, t3 = {c1.x - c3.x, c1.y - c3.y};
;   o0 = float2{t0.x + t2.x, t0.y + t2.y}; o2 = float2{t0.x - t2.x, t0.y - t2.y}; o1 = float2{t1.x - t3.y, t1.y + t3.x}; o3 = float2{t1.x + t3.y, t1.y - t3.x};
; }
;   for (int bb = tid; bb < NBT * (N / 4); bb += NTHR) { const int b = bb & (N / 4 - 1); float2* z = z0 + (bb / (N / 4)) * N; const int base = b * 4; f32x4 k01 = *(const f32x4*)(kh + base), k23 = *(const f32x4*)(kh + base + 2); float2 o0, o1, o2, o3;
;     bfly_inv(cmul(z[base], float2{k01[0], k01[1]}), cmul(z[base + 1], float2{k01[2], k01[3]}), cmul(z[base + 2], float2{k23[0], k23[1]}), cmul(z[base + 3], float2{k23[2], k23[3]}), 0.f, o0, o1, o2, o3);
;     z[base] = o0; z[base + 1] = o1; z[base + 2] = o2; z[base + 3] = o3; }
;   __syncthreads();
	v_pk_mul_f32 v[14:15], v[226:227], v[20:21] op_sel:[1,1] op_sel_hi:[0,1]
	s_nop 0
	v_pk_fma_f32 v[28:29], v[226:227], v[20:21], v[14:15] neg_lo:[0,0,1] neg_hi:[0,0,1]
	v_pk_fma_f32 v[226:227], v[226:227], v[20:21], v[14:15] op_sel_hi:[1,0,1]
	s_nop 0
	v_mov_b32_e32 v226, v23
	v_mov_b32_e32 v29, v227
	v_pk_mul_f32 v[226:227], v[228:229], v[226:227] op_sel:[1,0] op_sel_hi:[0,0]
	s_nop 0
	v_pk_fma_f32 v[14:15], v[228:229], v[22:23], v[226:227] op_sel_hi:[1,0,1] neg_lo:[0,0,1] neg_hi:[0,0,1]
	v_pk_fma_f32 v[226:227], v[228:229], v[22:23], v[226:227] op_sel_hi:[1,0,1]
	s_waitcnt lgkmcnt(0)
	v_pk_mul_f32 v[228:229], v[222:223], v[24:25] op_sel:[1,1] op_sel_hi:[0,1]
	s_nop 0
	v_pk_fma_f32 v[20:21], v[222:223], v[24:25], v[228:229] op_sel_hi:[1,0,1] neg_lo:[0,0,1] neg_hi:[0,0,1]
	v_pk_fma_f32 v[222:223], v[222:223], v[24:25], v[228:229] op_sel_hi:[1,0,1]
	v_mov_b32_e32 v228, v27
	v_pk_mul_f32 v[228:229], v[224:225], v[228:229] op_sel:[1,0] op_sel_hi:[0,0]
	s_nop 0
	v_pk_fma_f32 v[22:23], v[224:225], v[26:27], v[228:229] op_sel_hi:[1,0,1] neg_lo:[0,0,1] neg_hi:[0,0,1]
	v_pk_fma_f32 v[224:225], v[224:225], v[26:27], v[228:229] op_sel_hi:[1,0,1]
	v_pk_mov_b32 v[228:229], v[226:227], v[14:15] op_sel:[1,0]
	s_nop 0
	v_pk_fma_f32 v[14:15], v[228:229], 0, v[14:15] op_sel_hi:[1,0,1] neg_lo:[1,0,0] neg_hi:[1,0,0]
	v_pk_fma_f32 v[226:227], v[228:229], 0, v[226:227] op_sel_hi:[1,0,1]
	s_nop 0
	v_mov_b32_e32 v15, v227
	v_pk_mov_b32 v[226:227], v[222:223], v[20:21] op_sel:[1,0]
	s_nop 0
	v_pk_fma_f32 v[228:229], v[226:227], 0, v[20:21] op_sel_hi:[1,0,1] neg_lo:[1,0,0] neg_hi:[1,0,0]
	v_pk_fma_f32 v[222:223], v[226:227], 0, v[222:223] op_sel_hi:[1,0,1]
	s_nop 0
	v_mov_b32_e32 v229, v223
	v_pk_mov_b32 v[222:223], v[224:225], v[22:23] op_sel:[1,0]
	v_pk_add_f32 v[20:21], v[28:29], v[228:229]
	v_pk_fma_f32 v[226:227], v[222:223], 0, v[22:23] op_sel_hi:[1,0,1] neg_lo:[1,0,0] neg_hi:[1,0,0]
	v_pk_fma_f32 v[222:223], v[222:223], 0, v[224:225] op_sel_hi:[1,0,1]
	v_pk_add_f32 v[224:225], v[28:29], v[228:229] neg_lo:[0,1] neg_hi:[0,1]
	v_mov_b32_e32 v227, v223
	v_pk_add_f32 v[22:23], v[14:15], v[226:227]
	v_pk_add_f32 v[226:227], v[14:15], v[226:227] neg_lo:[0,1] neg_hi:[0,1]
	v_pk_add_f32 v[222:223], v[20:21], v[22:23]
	v_pk_add_f32 v[228:229], v[224:225], v[226:227] op_sel:[0,1] op_sel_hi:[1,0] neg_lo:[0,1] neg_hi:[0,1]
	v_pk_add_f32 v[226:227], v[224:225], v[226:227] op_sel:[0,1] op_sel_hi:[1,0]
	v_mov_b32_e32 v224, v228
	v_mov_b32_e32 v225, v227
	ds_write_b128 v19, v[222:225]
	v_add_u32_e32 v222, 0x200, v5
	v_pk_add_f32 v[224:225], v[20:21], v[22:23] neg_lo:[0,1] neg_hi:[0,1]
	v_mov_b32_e32 v227, v229
	v_mov_b32_e32 v5, v222
	ds_write_b128 v19, v[224:227] offset:16
	s_nop 0
	v_lshlrev_b32_e32 v219, 3, v218
	v_and_b32_e32 v220, 0x1ffe0, v219
	global_load_dwordx4 v[222:225], v220, s[80:81] offset:16
	global_load_dwordx4 v[226:229], v220, s[80:81]
	v_add_u32_e32 v218, 0x800, v218
	v_ashrrev_i32_e32 v6, 31, v5
	v_lshrrev_b32_e32 v6, 20, v6
	v_add_lshl_u32 v6, v5, v6, 5
	v_and_b32_e32 v14, 0xfffe0000, v6
	v_lshlrev_b32_e32 v6, 3, v4
	v_and_b32_e32 v15, 0x1ffe0, v6
	s_nop 0
	v_add3_u32 v19, 16, v14, v15
	ds_read_b128 v[20:23], v19
	ds_read_b128 v[24:27], v19 offset:16
	s_nop 0
	v_add_u32_e32 v4, 0x800, v4
	s_nop 0
	s_waitcnt vmcnt(4) lgkmcnt(1)
	v_pk_mul_f32 v[14:15], v[234:235], v[20:21] op_sel:[1,1] op_sel_hi:[0,1]
	s_nop 0
	v_pk_fma_f32 v[28:29], v[234:235], v[20:21], v[14:15] neg_lo:[0,0,1] neg_hi:[0,0,1]
	v_pk_fma_f32 v[234:235], v[234:235], v[20:21], v[14:15] op_sel_hi:[1,0,1]
	s_nop 0
	v_mov_b32_e32 v234, v23
	v_mov_b32_e32 v29, v235
	v_pk_mul_f32 v[234:235], v[236:237], v[234:235] op_sel:[1,0] op_sel_hi:[0,0]
	s_nop 0
	v_pk_fma_f32 v[14:15], v[236:237], v[22:23], v[234:235] op_sel_hi:[1,0,1] neg_lo:[0,0,1] neg_hi:[0,0,1]
	v_pk_fma_f32 v[234:235], v[236:237], v[22:23], v[234:235] op_sel_hi:[1,0,1]
	s_waitcnt lgkmcnt(0)
	v_pk_mul_f32 v[236:237], v[230:231], v[24:25] op_sel:[1,1] op_sel_hi:[0,1]
	s_nop 0
	v_pk_fma_f32 v[20:21], v[230:231], v[24:25], v[236:237] op_sel_hi:[1,0,1] neg_lo:[0,0,1] neg_hi:[0,0,1]
	v_pk_fma_f32 v[230:231], v[230:231], v[24:25], v[236:237] op_sel_hi:[1,0,1]
	v_mov_b32_e32 v236, v27
	v_pk_mul_f32 v[236:237], v[232:233], v[236:237] op_sel:[1,0] op_sel_hi:[0,0]
	s_nop 0
	v_pk_fma_f32 v[22:23], v[232:233], v[26:27], v[236:237] op_sel_hi:[1,0,1] neg_lo:[0,0,1] neg_hi:[0,0,1]
	v_pk_fma_f32 v[232:233], v[232:233], v[26:27], v[236:237] op_sel_hi:[1,0,1]
	v_pk_mov_b32 v[236:237], v[234:235], v[14:15] op_sel:[1,0]
	s_nop 0
	v_pk_fma_f32 v[14:15], v[236:237], 0, v[14:15] op_sel_hi:[1,0,1] neg_lo:[1,0,0] neg_hi:[1,0,0]
	v_pk_fma_f32 v[234:235], v[236:237], 0, v[234:235] op_sel_hi:[1,0,1]
	s_nop 0
	v_mov_b32_e32 v15, v235
	v_pk_mov_b32 v[234:235], v[230:231], v[20:21] op_sel:[1,0]
	s_nop 0
	v_pk_fma_f32 v[236:237], v[234:235], 0, v[20:21] op_sel_hi:[1,0,1] neg_lo:[1,0,0] neg_hi:[1,0,0]
	v_pk_fma_f32 v[230:231], v[234:235], 0, v[230:231] op_sel_hi:[1,0,1]
	s_nop 0
	v_mov_b32_e32 v237, v231
	v_pk_mov_b32 v[230:231], v[232:233], v[22:23] op_sel:[1,0]
	v_pk_add_f32 v[20:21], v[28:29], v[236:237]
	v_pk_fma_f32 v[234:235], v[230:231], 0, v[22:23] op_sel_hi:[1,0,1] neg_lo:[1,0,0] neg_hi:[1,0,0]
	v_pk_fma_f32 v[230:231], v[230:231], 0, v[232:233] op_sel_hi:[1,0,1]
	v_pk_add_f32 v[232:233], v[28:29], v[236:237] neg_lo:[0,1] neg_hi:[0,1]
	v_mov_b32_e32 v235, v231
	v_pk_add_f32 v[22:23], v[14:15], v[234:235]
	v_pk_add_f32 v[234:235], v[14:15], v[234:235] neg_lo:[0,1] neg_hi:[0,1]
	v_pk_add_f32 v[230:231], v[20:21], v[22:23]
	v_pk_add_f32 v[236:237], v[232:233], v[234:235] op_sel:[0,1] op_sel_hi:[1,0] neg_lo:[0,1] neg_hi:[0,1]
	v_pk_add_f32 v[234:235], v[232:233], v[234:235] op_sel:[0,1] op_sel_hi:[1,0]
	v_mov_b32_e32 v232, v236
	v_mov_b32_e32 v233, v235
	ds_write_b128 v19, v[230:233]
	v_add_u32_e32 v230, 0x200, v5
	v_pk_add_f32 v[232:233], v[20:21], v[22:23] neg_lo:[0,1] neg_hi:[0,1]
	v_mov_b32_e32 v235, v237
	v_mov_b32_e32 v5, v230
	ds_write_b128 v19, v[232:235] offset:16
	s_nop 0
	v_lshlrev_b32_e32 v219, 3, v218
	v_and_b32_e32 v220, 0x1ffe0, v219
	global_load_dwordx4 v[230:233], v220, s[80:81] offset:16
	global_load_dwordx4 v[234:237], v220, s[80:81]
	v_add_u32_e32 v218, 0x800, v218
	v_ashrrev_i32_e32 v6, 31, v5
	v_lshrrev_b32_e32 v6, 20, v6
	v_add_lshl_u32 v6, v5, v6, 5
	v_and_b32_e32 v14, 0xfffe0000, v6
	v_lshlrev_b32_e32 v6, 3, v4
	v_and_b32_e32 v15, 0x1ffe0, v6
	s_nop 0
	v_add3_u32 v19, 16, v14, v15
	ds_read_b128 v[20:23], v19
	ds_read_b128 v[24:27], v19 offset:16
	s_nop 0
	v_add_u32_e32 v4, 0x800, v4
	s_nop 0
	s_waitcnt vmcnt(4) lgkmcnt(1)
; DI float2 twid(float r) { return float2{__builtin_amdgcn_cosf(r), -__builtin_amdgcn_sinf(r)}; }
; DI void bfly_inv(float2 s0, float2 s1, float2 s2, float2 s3, float r, float2& o0, float2& o1, float2& o2, float2& o3) {
;   float2 w1 = twid(r), w2 = cmul(w1, w1), w3 = cmul(w2, w1);
;   float2 c0 = s0, c1 = cmulc(s1, w1), c2 = cmulc(s2, w2), c3 = cmulc(s3, w3);
;   float2 t0 = {c0.x + c2.x, c0.y + c2.y}, t1 = {c0.x - c2.x, c0.y - c2.y}, t2 = {c1.x + c3.x, c1.y + c3.y}, t3 = {c1.x - c3.x, c1.y - c3.y};
;   o0 = float2{t0.x + t2.x, t0.y + t2.y}; o2 = float2{t0.x - t2.x, t0.y - t2.y}; o1 = float2{t1.x - t3.y, t1.y + t3.x}; o3 = float2{t1.x + t3.y, t1.y - t3.x};
; }
;   for (int bb = tid; bb < NBT * (N / 4); bb += NTHR) { const int b = bb & (N / 4 - 1); float2* z = z0 + (bb / (N / 4)) * N; const int base = b * 4; f32x4 k01 = *(const f32x4*)(kh + base), k23 = *(const f32x4*)(kh + base + 2); float2 o0, o1, o2, o3;
;     bfly_inv(cmul(z[base], float2{k01[0], k01[1]}), cmul(z[base + 1], float2{k01[2], k01[3]}), cmul(z[base + 2], float2{k23[0], k23[1]}), cmul(z[base + 3], float2{k23[2], k23[3]}), 0.f, o0, o1, o2, o3);
;     z[base] = o0; z[base + 1] = o1; z[base + 2] = o2; z[base + 3] = o3; }
;   __syncthreads();
	v_pk_mul_f32 v[14:15], v[246:247], v[20:21] op_sel:[1,1] op_sel_hi:[0,1]
	s_nop 0
	v_pk_fma_f32 v[28:29], v[246:247], v[20:21], v[14:15] neg_lo:[0,0,1] neg_hi:[0,0,1]
	v_pk_fma_f32 v[246:247], v[246:247], v[20:21], v[14:15] op_sel_hi:[1,0,1]
	s_nop 0
	v_mov_b32_e32 v246, v23
	v_mov_b32_e32 v29, v247
	v_pk_mul_f32 v[246:247], v[248:249], v[246:247] op_sel:[1,0] op_sel_hi:[0,0]
	s_nop 0
	v_pk_fma_f32 v[14:15], v[248:249], v[22:23], v[246:247] op_sel_hi:[1,0,1] neg_lo:[0,0,1] neg_hi:[0,0,1]
	v_pk_fma_f32 v[246:247], v[248:249], v[22:23], v[246:247] op_sel_hi:[1,0,1]
	s_waitcnt lgkmcnt(0)
	v_pk_mul_f32 v[248:249], v[242:243], v[24:25] op_sel:[1,1] op_sel_hi:[0,1]
	s_nop 0
	v_pk_fma_f32 v[20:21], v[242:243], v[24:25], v[248:249] op_sel_hi:[1,0,1] neg_lo:[0,0,1] neg_hi:[0,0,1]
	v_pk_fma_f32 v[242:243], v[242:243], v[24:25], v[248:249] op_sel_hi:[1,0,1]
	v_mov_b32_e32 v248, v27
	v_pk_mul_f32 v[248:249], v[244:245], v[248:249] op_sel:[1,0] op_sel_hi:[0,0]
	s_nop 0
	v_pk_fma_f32 v[22:23], v[244:245], v[26:27], v[248:249] op_sel_hi:[1,0,1] neg_lo:[0,0,1] neg_hi:[0,0,1]
	v_pk_fma_f32 v[244:245], v[244:245], v[26:27], v[248:249] op_sel_hi:[1,0,1]
	v_pk_mov_b32 v[248:249], v[246:247], v[14:15] op_sel:[1,0]
	s_nop 0
	v_pk_fma_f32 v[14:15], v[248:249], 0, v[14:15] op_sel_hi:[1,0,1] neg_lo:[1,0,0] neg_hi:[1,0,0]
	v_pk_fma_f32 v[246:247], v[248:249], 0, v[246:247] op_sel_hi:[1,0,1]
	s_nop 0
	v_mov_b32_e32 v15, v247
	v_pk_mov_b32 v[246:247], v[242:243], v[20:21] op_sel:[1,0]
	s_nop 0
	v_pk_fma_f32 v[248:249], v[246:247], 0, v[20:21] op_sel_hi:[1,0,1] neg_lo:[1,0,0] neg_hi:[1,0,0]
	v_pk_fma_f32 v[242:243], v[246:247], 0, v[242:243] op_sel_hi:[1,0,1]
	s_nop 0
	v_mov_b32_e32 v249, v243
	v_pk_mov_b32 v[242:243], v[244:245], v[22:23] op_sel:[1,0]
	v_pk_add_f32 v[20:21], v[28:29], v[248:249]
	v_pk_fma_f32 v[246:247], v[242:243], 0, v[22:23] op_sel_hi:[1,0,1] neg_lo:[1,0,0] neg_hi:[1,0,0]
	v_pk_fma_f32 v[242:243], v[242:243], 0, v[244:245] op_sel_hi:[1,0,1]
	v_pk_add_f32 v[244:245], v[28:29], v[248:249] neg_lo:[0,1] neg_hi:[0,1]
	v_mov_b32_e32 v247, v243
	v_pk_add_f32 v[22:23], v[14:15], v[246:247]
	v_pk_add_f32 v[246:247], v[14:15], v[246:247] neg_lo:[0,1] neg_hi:[0,1]
	v_pk_add_f32 v[242:243], v[20:21], v[22:23]
	v_pk_add_f32 v[248:249], v[244:245], v[246:247] op_sel:[0,1] op_sel_hi:[1,0] neg_lo:[0,1] neg_hi:[0,1]
	v_pk_add_f32 v[246:247], v[244:245], v[246:247] op_sel:[0,1] op_sel_hi:[1,0]
	v_mov_b32_e32 v244, v248
	v_mov_b32_e32 v245, v247
	ds_write_b128 v19, v[242:245]
	v_add_u32_e32 v242, 0x200, v5
	v_pk_add_f32 v[244:245], v[20:21], v[22:23] neg_lo:[0,1] neg_hi:[0,1]
	v_mov_b32_e32 v247, v249
	v_mov_b32_e32 v5, v242
	ds_write_b128 v19, v[244:247] offset:16
	s_nop 0
	v_ashrrev_i32_e32 v6, 31, v5
	v_lshrrev_b32_e32 v6, 20, v6
	v_add_lshl_u32 v6, v5, v6, 5
	v_and_b32_e32 v14, 0xfffe0000, v6
	v_lshlrev_b32_e32 v6, 3, v4
	v_and_b32_e32 v15, 0x1ffe0, v6
	s_nop 0
	v_add3_u32 v19, 16, v14, v15
	ds_read_b128 v[20:23], v19
	ds_read_b128 v[24:27], v19 offset:16
	s_nop 0
	v_add_u32_e32 v4, 0x800, v4
	s_nop 0
	s_waitcnt vmcnt(2) lgkmcnt(1)
	v_pk_mul_f32 v[14:15], v[226:227], v[20:21] op_sel:[1,1] op_sel_hi:[0,1]
	s_nop 0
	v_pk_fma_f32 v[28:29], v[226:227], v[20:21], v[14:15] neg_lo:[0,0,1] neg_hi:[0,0,1]
	v_pk_fma_f32 v[226:227], v[226:227], v[20:21], v[14:15] op_sel_hi:[1,0,1]
	s_nop 0
	v_mov_b32_e32 v226, v23
	v_mov_b32_e32 v29, v227
	v_pk_mul_f32 v[226:227], v[228:229], v[226:227] op_sel:[1,0] op_sel_hi:[0,0]
	s_nop 0
	v_pk_fma_f32 v[14:15], v[228:229], v[22:23], v[226:227] op_sel_hi:[1,0,1] neg_lo:[0,0,1] neg_hi:[0,0,1]
	v_pk_fma_f32 v[226:227], v[228:229], v[22:23], v[226:227] op_sel_hi:[1,0,1]
	s_waitcnt lgkmcnt(0)
; DI float2 twid(float r) { return float2{__builtin_amdgcn_cosf(r), -__builtin_amdgcn_sinf(r)}; }
; DI void bfly_inv(float2 s0, float2 s1, float2 s2, float2 s3, float r, float2& o0, float2& o1, float2& o2, float2& o3) {
;   float2 w1 = twid(r), w2 = cmul(w1, w1), w3 = cmul(w2, w1);
;   float2 c0 = s0, c1 = cmulc(s1, w1), c2 = cmulc(s2, w2), c3 = cmulc(s3, w3);
;   float2 t0 = {c0.x + c2.x, c0.y + c2.y}, t1 = {c0.x - c2.x, c0.y - c2.y}, t2 = {c1.x + c3.x, c1.y + c3.y}, t3 = {c1.x - c3.x, c1.y - c3.y};
;   o0 = float2{t0.x + t2.x, t0.y + t2.y}; o2 = float2{t0.x - t2.x, t0.y - t2.y}; o1 = float2{t1.x - t3.y, t1.y + t3.x}; o3 = float2{t1.x + t3.y, t1.y - t3.x};
; }
;   for (int bb = tid; bb < NBT * (N / 4); bb += NTHR) { const int b = bb & (N / 4 - 1); float2* z = z0 + (bb / (N / 4)) * N; const int base = b * 4; f32x4 k01 = *(const f32x4*)(kh + base), k23 = *(const f32x4*)(kh + base + 2); float2 o0, o1, o2, o3;
;     bfly_inv(cmul(z[base], float2{k01[0], k01[1]}), cmul(z[base + 1], float2{k01[2], k01[3]}), cmul(z[base + 2], float2{k23[0], k23[1]}), cmul(z[base + 3], float2{k23[2], k23[3]}), 0.f, o0, o1, o2, o3);
;     z[base] = o0; z[base + 1] = o1; z[base + 2] = o2; z[base + 3] = o3; }
;   __syncthreads();
	v_pk_mul_f32 v[228:229], v[222:223], v[24:25] op_sel:[1,1] op_sel_hi:[0,1]
	s_nop 0
	v_pk_fma_f32 v[20:21], v[222:223], v[24:25], v[228:229] op_sel_hi:[1,0,1] neg_lo:[0,0,1] neg_hi:[0,0,1]
	v_pk_fma_f32 v[222:223], v[222:223], v[24:25], v[228:229] op_sel_hi:[1,0,1]
	v_mov_b32_e32 v228, v27
	v_pk_mul_f32 v[228:229], v[224:225], v[228:229] op_sel:[1,0] op_sel_hi:[0,0]
	s_nop 0
	v_pk_fma_f32 v[22:23], v[224:225], v[26:27], v[228:229] op_sel_hi:[1,0,1] neg_lo:[0,0,1] neg_hi:[0,0,1]
	v_pk_fma_f32 v[224:225], v[224:225], v[26:27], v[228:229] op_sel_hi:[1,0,1]
	v_pk_mov_b32 v[228:229], v[226:227], v[14:15] op_sel:[1,0]
	s_nop 0
	v_pk_fma_f32 v[14:15], v[228:229], 0, v[14:15] op_sel_hi:[1,0,1] neg_lo:[1,0,0] neg_hi:[1,0,0]
	v_pk_fma_f32 v[226:227], v[228:229], 0, v[226:227] op_sel_hi:[1,0,1]
	s_nop 0
	v_mov_b32_e32 v15, v227
	v_pk_mov_b32 v[226:227], v[222:223], v[20:21] op_sel:[1,0]
	s_nop 0
	v_pk_fma_f32 v[228:229], v[226:227], 0, v[20:21] op_sel_hi:[1,0,1] neg_lo:[1,0,0] neg_hi:[1,0,0]
	v_pk_fma_f32 v[222:223], v[226:227], 0, v[222:223] op_sel_hi:[1,0,1]
	s_nop 0
	v_mov_b32_e32 v229, v223
	v_pk_mov_b32 v[222:223], v[224:225], v[22:23] op_sel:[1,0]
	v_pk_add_f32 v[20:21], v[28:29], v[228:229]
	v_pk_fma_f32 v[226:227], v[222:223], 0, v[22:23] op_sel_hi:[1,0,1] neg_lo:[1,0,0] neg_hi:[1,0,0]
	v_pk_fma_f32 v[222:223], v[222:223], 0, v[224:225] op_sel_hi:[1,0,1]
	v_pk_add_f32 v[224:225], v[28:29], v[228:229] neg_lo:[0,1] neg_hi:[0,1]
	v_mov_b32_e32 v227, v223
	v_pk_add_f32 v[22:23], v[14:15], v[226:227]
	v_pk_add_f32 v[226:227], v[14:15], v[226:227] neg_lo:[0,1] neg_hi:[0,1]
	v_pk_add_f32 v[222:223], v[20:21], v[22:23]
	v_pk_add_f32 v[228:229], v[224:225], v[226:227] op_sel:[0,1] op_sel_hi:[1,0] neg_lo:[0,1] neg_hi:[0,1]
	v_pk_add_f32 v[226:227], v[224:225], v[226:227] op_sel:[0,1] op_sel_hi:[1,0]
	v_mov_b32_e32 v224, v228
	v_mov_b32_e32 v225, v227
	ds_write_b128 v19, v[222:225]
	v_add_u32_e32 v222, 0x200, v5
	v_pk_add_f32 v[224:225], v[20:21], v[22:23] neg_lo:[0,1] neg_hi:[0,1]
	v_mov_b32_e32 v227, v229
	v_mov_b32_e32 v5, v222
	ds_write_b128 v19, v[224:227] offset:16
	s_nop 0
	v_ashrrev_i32_e32 v6, 31, v5
	v_lshrrev_b32_e32 v6, 20, v6
	v_add_lshl_u32 v6, v5, v6, 5
	v_and_b32_e32 v14, 0xfffe0000, v6
	v_lshlrev_b32_e32 v6, 3, v4
	v_and_b32_e32 v15, 0x1ffe0, v6
	s_nop 0
	v_add3_u32 v19, 16, v14, v15
	ds_read_b128 v[20:23], v19
	ds_read_b128 v[24:27], v19 offset:16
	s_nop 0
	v_add_u32_e32 v4, 0x800, v4
	s_nop 0
	s_waitcnt vmcnt(0) lgkmcnt(1)
	v_pk_mul_f32 v[14:15], v[234:235], v[20:21] op_sel:[1,1] op_sel_hi:[0,1]
	s_nop 0
	v_pk_fma_f32 v[28:29], v[234:235], v[20:21], v[14:15] neg_lo:[0,0,1] neg_hi:[0,0,1]
	v_pk_fma_f32 v[234:235], v[234:235], v[20:21], v[14:15] op_sel_hi:[1,0,1]
	s_nop 0
	v_mov_b32_e32 v234, v23
	v_mov_b32_e32 v29, v235
	v_pk_mul_f32 v[234:235], v[236:237], v[234:235] op_sel:[1,0] op_sel_hi:[0,0]
	s_nop 0
	v_pk_fma_f32 v[14:15], v[236:237], v[22:23], v[234:235] op_sel_hi:[1,0,1] neg_lo:[0,0,1] neg_hi:[0,0,1]
	v_pk_fma_f32 v[234:235], v[236:237], v[22:23], v[234:235] op_sel_hi:[1,0,1]
	s_waitcnt lgkmcnt(0)
	v_pk_mul_f32 v[236:237], v[230:231], v[24:25] op_sel:[1,1] op_sel_hi:[0,1]
	s_nop 0
	v_pk_fma_f32 v[20:21], v[230:231], v[24:25], v[236:237] op_sel_hi:[1,0,1] neg_lo:[0,0,1] neg_hi:[0,0,1]
	v_pk_fma_f32 v[230:231], v[230:231], v[24:25], v[236:237] op_sel_hi:[1,0,1]
	v_mov_b32_e32 v236, v27
	v_pk_mul_f32 v[236:237], v[232:233], v[236:237] op_sel:[1,0] op_sel_hi:[0,0]
	s_nop 0
	v_pk_fma_f32 v[22:23], v[232:233], v[26:27], v[236:237] op_sel_hi:[1,0,1] neg_lo:[0,0,1] neg_hi:[0,0,1]
	v_pk_fma_f32 v[232:233], v[232:233], v[26:27], v[236:237] op_sel_hi:[1,0,1]
	v_pk_mov_b32 v[236:237], v[234:235], v[14:15] op_sel:[1,0]
	s_nop 0
	v_pk_fma_f32 v[14:15], v[236:237], 0, v[14:15] op_sel_hi:[1,0,1] neg_lo:[1,0,0] neg_hi:[1,0,0]
	v_pk_fma_f32 v[234:235], v[236:237], 0, v[234:235] op_sel_hi:[1,0,1]
	s_nop 0
	v_mov_b32_e32 v15, v235
	v_pk_mov_b32 v[234:235], v[230:231], v[20:21] op_sel:[1,0]
	s_nop 0
	v_pk_fma_f32 v[236:237], v[234:235], 0, v[20:21] op_sel_hi:[1,0,1] neg_lo:[1,0,0] neg_hi:[1,0,0]
	v_pk_fma_f32 v[230:231], v[234:235], 0, v[230:231] op_sel_hi:[1,0,1]
	s_nop 0
	v_mov_b32_e32 v237, v231
	v_pk_mov_b32 v[230:231], v[232:233], v[22:23] op_sel:[1,0]
	v_pk_add_f32 v[20:21], v[28:29], v[236:237]
	v_pk_fma_f32 v[234:235], v[230:231], 0, v[22:23] op_sel_hi:[1,0,1] neg_lo:[1,0,0] neg_hi:[1,0,0]
	v_pk_fma_f32 v[230:231], v[230:231], 0, v[232:233] op_sel_hi:[1,0,1]
	v_pk_add_f32 v[232:233], v[28:29], v[236:237] neg_lo:[0,1] neg_hi:[0,1]
	v_mov_b32_e32 v235, v231
	v_pk_add_f32 v[22:23], v[14:15], v[234:235]
	v_pk_add_f32 v[234:235], v[14:15], v[234:235] neg_lo:[0,1] neg_hi:[0,1]
	v_pk_add_f32 v[230:231], v[20:21], v[22:23]
	v_pk_add_f32 v[236:237], v[232:233], v[234:235] op_sel:[0,1] op_sel_hi:[1,0] neg_lo:[0,1] neg_hi:[0,1]
	v_pk_add_f32 v[234:235], v[232:233], v[234:235] op_sel:[0,1] op_sel_hi:[1,0]
	v_mov_b32_e32 v232, v236
	v_mov_b32_e32 v233, v235
	ds_write_b128 v19, v[230:233]
	v_add_u32_e32 v230, 0x200, v5
	v_pk_add_f32 v[232:233], v[20:21], v[22:23] neg_lo:[0,1] neg_hi:[0,1]
	v_mov_b32_e32 v235, v237
	v_mov_b32_e32 v5, v230
	ds_write_b128 v19, v[232:235] offset:16
	s_nop 0
	s_mov_b64 s[84:85], exec
